# FFN GEMM loops: MFMA order acc-major (k0,k1 back-to-back on the same accumulator; SrcC forwarding / power experiment)
# speedup vs baseline: 1.0108x; 1.0108x over previous
;     __device__ __forceinline__ size_t a_koff(int t) const { return (size_t)t * 128; }
;     __device__ __forceinline__ size_t a_koff(int t) const { return (size_t)t * 32768; }
; #define PG8_STAGE(bufoff, gbase, voff) do { _Pragma("unroll") for (int _i = 0; _i < 2; ++_i) \
;         __builtin_amdgcn_global_load_lds((const unsigned*)((const char*)(gbase) + (size_t)_i * p##voff + (voff)), (LAS unsigned*)(lds + (bufoff) + ldsw + _i * 8192), 16, 0, 0); } while (0)
; #define PG8_LDA(dst, b, h) do { _Pragma("unroll") for (int m = 0; m < 4; ++m) _Pragma("unroll") for (int k = 0; k < 2; ++k) dst[m][k] = *(const LAS bf16x8*)(lds + PG8_SA(b, h) + aoff + m * 2048 + k * 1024); } while (0)
; #define PG8_LDB(dst, b, h) do { _Pragma("unroll") for (int n = 0; n < 2; ++n) _Pragma("unroll") for (int k = 0; k < 2; ++k) dst[n][k] = *(const LAS bf16x8*)(lds + PG8_SB(b, h) + boff + n * 2048 + k * 1024); } while (0)
; #define PG8_WAIT_V(n) asm volatile("s_waitcnt vmcnt(" #n ")" ::: "memory")
; #define PG8_WAIT_L(n) asm volatile("s_waitcnt lgkmcnt(" #n ")" ::: "memory")
; #define PG8_BAR __builtin_amdgcn_s_barrier()
; #define PG8_SCHED __builtin_amdgcn_sched_barrier(0)
;     __device__ __forceinline__ size_t a_koff(int t) const { return ((size_t)(t >> 1) * 3072 + (size_t)(t & 1) * 64) * 2; }
;     __device__ __forceinline__ size_t a_koff(int t) const { return (size_t)t * 128; }
;     ...
;         for (int t = 0; t < nt; t += 2) {
;             const bool last = (t == nt - 2);
;             const char* a1 = cA + g.a_koff(t + 1);
;             const char* a2 = last ? nA : cA + g.a_koff(t + 2); const char* b2 = last ? nB : cB + (size_t)(t + 2) * kstep;
;             const char* a3 = last ? nA + g.a_koff(1) : cA + g.a_koff(t + 3); const char* b3 = b2 + kstep;
;             PG8_LDB(B0, 0, 0); PG8_LDB(B1, 0, 1); PG8_SCHED; PG8_LDA(At, 0, 0); PG8_STAGE(PG8_SA(1, 1), a1 + hstepA, voffA);
;             PG8_WAIT_V(8); PG8_WAIT_L(0); PG8_BAR; PG8_MMA(0, 0, At, B0); PG8_MMA(0, 1, At, B1); PG8_BAR; PG8_SCHED;
;             PG8_LDA(At, 0, 1); PG8_STAGE(PG8_SB(0, 0), b2, voffB); PG8_STAGE(PG8_SB(0, 1), b2 + hstepB, voffB); PG8_STAGE(PG8_SA(0, 0), a2, voffA);
;             PG8_WAIT_V(8); PG8_WAIT_L(0); PG8_BAR; PG8_MMA(1, 0, At, B0); PG8_MMA(1, 1, At, B1); PG8_BAR; PG8_SCHED;
.LBB0_1206:
	ds_read_b128 v[148:151], v144
	ds_read_b128 v[152:155], v144 offset:1024
	ds_read_b128 v[156:159], v144 offset:2048
	ds_read_b128 v[160:163], v144 offset:3072
	ds_read_b128 v[164:167], v145
	ds_read_b128 v[168:171], v145 offset:1024
	ds_read_b128 v[172:175], v145 offset:2048
	ds_read_b128 v[176:179], v145 offset:3072
	s_add_u32 s46, s42, s44
	s_addc_u32 s47, s43, s45
	s_add_u32 s74, s46, 0x10000
	s_addc_u32 s75, s47, 0
	s_add_u32 s46, s46, 0x18000
	s_addc_u32 s47, s47, 0
	s_cmp_eq_u32 s44, 0x1f0000
	s_cselect_b32 s47, s68, s47
	s_cselect_b32 s46, s67, s46
	s_cselect_b32 s73, s29, s70
	s_cselect_b32 s72, s66, s69
	s_cselect_b32 s75, s35, s75
	s_cselect_b32 s74, s65, s74
	v_lshl_add_u64 v[184:185], v[142:143], 0, s[44:45]
	v_lshl_add_u64 v[216:217], v[184:185], 0, s[76:77]
	s_add_i32 m0, s52, 0xc000
	ds_read_b128 v[180:183], v146
	ds_read_b128 v[188:191], v146 offset:1024
	ds_read_b128 v[192:195], v146 offset:2048
	ds_read_b128 v[196:199], v146 offset:3072
	ds_read_b128 v[200:203], v146 offset:4096
	ds_read_b128 v[204:207], v146 offset:5120
	ds_read_b128 v[208:211], v146 offset:6144
	ds_read_b128 v[212:215], v146 offset:7168
	global_load_lds_dwordx4 v[216:217], off
	v_lshl_add_u64 v[184:185], v[184:185], 0, s[26:27]
	s_add_i32 m0, s52, 0xe000
	s_nop 0
	global_load_lds_dwordx4 v[184:185], off
	s_waitcnt vmcnt(8)
	s_waitcnt lgkmcnt(0)
	s_barrier
	s_setprio 1
	s_waitcnt lgkmcnt(0)
	v_mfma_f32_16x16x32_bf16 v[126:129], v[148:151], v[180:183], v[126:129]
	v_mfma_f32_16x16x32_bf16 v[126:129], v[152:155], v[188:191], v[126:129]
	v_mfma_f32_16x16x32_bf16 v[122:125], v[156:159], v[180:183], v[122:125]
	v_mfma_f32_16x16x32_bf16 v[122:125], v[160:163], v[188:191], v[122:125]
	v_mfma_f32_16x16x32_bf16 v[110:113], v[148:151], v[192:195], v[110:113]
	v_mfma_f32_16x16x32_bf16 v[110:113], v[152:155], v[196:199], v[110:113]
	v_mfma_f32_16x16x32_bf16 v[106:109], v[156:159], v[192:195], v[106:109]
	v_mfma_f32_16x16x32_bf16 v[106:109], v[160:163], v[196:199], v[106:109]
	v_mfma_f32_16x16x32_bf16 v[94:97], v[148:151], v[200:203], v[94:97]
	v_mfma_f32_16x16x32_bf16 v[94:97], v[152:155], v[204:207], v[94:97]
	v_mfma_f32_16x16x32_bf16 v[90:93], v[156:159], v[200:203], v[90:93]
	v_mfma_f32_16x16x32_bf16 v[90:93], v[160:163], v[204:207], v[90:93]
	v_mfma_f32_16x16x32_bf16 v[78:81], v[148:151], v[208:211], v[78:81]
	v_mfma_f32_16x16x32_bf16 v[78:81], v[152:155], v[212:215], v[78:81]
	v_mfma_f32_16x16x32_bf16 v[74:77], v[156:159], v[208:211], v[74:77]
	v_mfma_f32_16x16x32_bf16 v[74:77], v[160:163], v[212:215], v[74:77]
	s_setprio 0
	s_setprio 1
	v_mfma_f32_16x16x32_bf16 v[118:121], v[164:167], v[180:183], v[118:121]
	v_mfma_f32_16x16x32_bf16 v[118:121], v[168:171], v[188:191], v[118:121]
	v_mfma_f32_16x16x32_bf16 v[114:117], v[172:175], v[180:183], v[114:117]
	v_mfma_f32_16x16x32_bf16 v[114:117], v[176:179], v[188:191], v[114:117]
	v_mfma_f32_16x16x32_bf16 v[102:105], v[164:167], v[192:195], v[102:105]
	v_mfma_f32_16x16x32_bf16 v[102:105], v[168:171], v[196:199], v[102:105]
	v_mfma_f32_16x16x32_bf16 v[98:101], v[172:175], v[192:195], v[98:101]
	v_mfma_f32_16x16x32_bf16 v[98:101], v[176:179], v[196:199], v[98:101]
	v_mfma_f32_16x16x32_bf16 v[86:89], v[164:167], v[200:203], v[86:89]
	v_mfma_f32_16x16x32_bf16 v[86:89], v[168:171], v[204:207], v[86:89]
	v_mfma_f32_16x16x32_bf16 v[82:85], v[172:175], v[200:203], v[82:85]
	v_mfma_f32_16x16x32_bf16 v[82:85], v[176:179], v[204:207], v[82:85]
	v_mfma_f32_16x16x32_bf16 v[70:73], v[164:167], v[208:211], v[70:73]
	v_mfma_f32_16x16x32_bf16 v[70:73], v[168:171], v[212:215], v[70:73]
	v_mfma_f32_16x16x32_bf16 v[66:69], v[172:175], v[208:211], v[66:69]
	v_mfma_f32_16x16x32_bf16 v[66:69], v[176:179], v[212:215], v[66:69]
	s_setprio 0
	s_barrier
	v_lshl_add_u64 v[184:185], s[72:73], 0, v[132:133]
	s_add_i32 s72, s63, s50
	s_mov_b32 m0, s72
	ds_read_b128 v[180:183], v146 offset:16384
	ds_read_b128 v[188:191], v146 offset:17408
	ds_read_b128 v[192:195], v146 offset:18432
	ds_read_b128 v[196:199], v146 offset:19456
	ds_read_b128 v[200:203], v146 offset:20480
	ds_read_b128 v[204:207], v146 offset:21504
	ds_read_b128 v[208:211], v146 offset:22528
	ds_read_b128 v[212:215], v146 offset:23552
	global_load_lds_dwordx4 v[184:185], off
	v_lshl_add_u64 v[216:217], v[184:185], 0, s[4:5]
	s_add_i32 m0, s72, 0x2000
	s_add_i32 s72, s64, s50
	global_load_lds_dwordx4 v[216:217], off
	v_lshl_add_u64 v[216:217], v[184:185], 0, s[6:7]
	s_mov_b32 m0, s72
	s_nop 0
	global_load_lds_dwordx4 v[216:217], off
	v_lshl_add_u64 v[216:217], v[184:185], 0, s[8:9]
	s_add_i32 m0, s72, 0x2000
	s_nop 0
	global_load_lds_dwordx4 v[216:217], off
	v_lshl_add_u64 v[216:217], s[74:75], 0, v[130:131]
	s_mov_b32 m0, s52
	v_lshl_add_u64 v[218:219], v[216:217], 0, s[10:11]
	global_load_lds_dwordx4 v[216:217], off
	s_mov_b32 m0, s53
	s_nop 0
	global_load_lds_dwordx4 v[218:219], off
	s_waitcnt vmcnt(8)
	s_waitcnt lgkmcnt(0)
	s_barrier
; #define PG8_STAGE(bufoff, gbase, voff) do { _Pragma("unroll") for (int _i = 0; _i < 2; ++_i) \
;         __builtin_amdgcn_global_load_lds((const unsigned*)((const char*)(gbase) + (size_t)_i * p##voff + (voff)), (LAS unsigned*)(lds + (bufoff) + ldsw + _i * 8192), 16, 0, 0); } while (0)
; #define PG8_LDA(dst, b, h) do { _Pragma("unroll") for (int m = 0; m < 4; ++m) _Pragma("unroll") for (int k = 0; k < 2; ++k) dst[m][k] = *(const LAS bf16x8*)(lds + PG8_SA(b, h) + aoff + m * 2048 + k * 1024); } while (0)
; #define PG8_LDB(dst, b, h) do { _Pragma("unroll") for (int n = 0; n < 2; ++n) _Pragma("unroll") for (int k = 0; k < 2; ++k) dst[n][k] = *(const LAS bf16x8*)(lds + PG8_SB(b, h) + boff + n * 2048 + k * 1024); } while (0)
; #define PG8_WAIT_V(n) asm volatile("s_waitcnt vmcnt(" #n ")" ::: "memory")
; #define PG8_WAIT_L(n) asm volatile("s_waitcnt lgkmcnt(" #n ")" ::: "memory")
; #define PG8_BAR __builtin_amdgcn_s_barrier()
; #define PG8_SCHED __builtin_amdgcn_sched_barrier(0)
;     ...
;             PG8_WAIT_V(8); PG8_WAIT_L(0); PG8_BAR; PG8_MMA(1, 0, At, B0); PG8_MMA(1, 1, At, B1); PG8_BAR; PG8_SCHED;
;             PG8_LDB(B0, 1, 0); PG8_LDB(B1, 1, 1); PG8_SCHED; PG8_LDA(At, 1, 0); PG8_STAGE(PG8_SA(0, 1), a2 + hstepA, voffA);
;             PG8_WAIT_V(8); PG8_WAIT_L(0); PG8_BAR; PG8_MMA(0, 0, At, B0); PG8_MMA(0, 1, At, B1); PG8_BAR; PG8_SCHED;
	s_setprio 1
	s_waitcnt lgkmcnt(0)
	v_mfma_f32_16x16x32_bf16 v[62:65], v[148:151], v[180:183], v[62:65]
	v_mfma_f32_16x16x32_bf16 v[62:65], v[152:155], v[188:191], v[62:65]
	v_mfma_f32_16x16x32_bf16 v[58:61], v[156:159], v[180:183], v[58:61]
	v_mfma_f32_16x16x32_bf16 v[58:61], v[160:163], v[188:191], v[58:61]
	v_mfma_f32_16x16x32_bf16 v[46:49], v[148:151], v[192:195], v[46:49]
	v_mfma_f32_16x16x32_bf16 v[46:49], v[152:155], v[196:199], v[46:49]
	v_mfma_f32_16x16x32_bf16 v[42:45], v[156:159], v[192:195], v[42:45]
	v_mfma_f32_16x16x32_bf16 v[42:45], v[160:163], v[196:199], v[42:45]
	v_mfma_f32_16x16x32_bf16 v[30:33], v[148:151], v[200:203], v[30:33]
	v_mfma_f32_16x16x32_bf16 v[30:33], v[152:155], v[204:207], v[30:33]
	v_mfma_f32_16x16x32_bf16 v[26:29], v[156:159], v[200:203], v[26:29]
	v_mfma_f32_16x16x32_bf16 v[26:29], v[160:163], v[204:207], v[26:29]
	v_mfma_f32_16x16x32_bf16 v[14:17], v[148:151], v[208:211], v[14:17]
	v_mfma_f32_16x16x32_bf16 v[14:17], v[152:155], v[212:215], v[14:17]
	v_mfma_f32_16x16x32_bf16 v[10:13], v[156:159], v[208:211], v[10:13]
	v_mfma_f32_16x16x32_bf16 v[10:13], v[160:163], v[212:215], v[10:13]
	s_setprio 0
	s_setprio 1
	v_mfma_f32_16x16x32_bf16 v[54:57], v[164:167], v[180:183], v[54:57]
	v_mfma_f32_16x16x32_bf16 v[54:57], v[168:171], v[188:191], v[54:57]
	v_mfma_f32_16x16x32_bf16 v[50:53], v[172:175], v[180:183], v[50:53]
	v_mfma_f32_16x16x32_bf16 v[50:53], v[176:179], v[188:191], v[50:53]
	v_mfma_f32_16x16x32_bf16 v[38:41], v[164:167], v[192:195], v[38:41]
	v_mfma_f32_16x16x32_bf16 v[38:41], v[168:171], v[196:199], v[38:41]
	v_mfma_f32_16x16x32_bf16 v[34:37], v[172:175], v[192:195], v[34:37]
	v_mfma_f32_16x16x32_bf16 v[34:37], v[176:179], v[196:199], v[34:37]
	v_mfma_f32_16x16x32_bf16 v[22:25], v[164:167], v[200:203], v[22:25]
	v_mfma_f32_16x16x32_bf16 v[22:25], v[168:171], v[204:207], v[22:25]
	v_mfma_f32_16x16x32_bf16 v[18:21], v[172:175], v[200:203], v[18:21]
	v_mfma_f32_16x16x32_bf16 v[18:21], v[176:179], v[204:207], v[18:21]
	v_mfma_f32_16x16x32_bf16 v[6:9], v[164:167], v[208:211], v[6:9]
	v_mfma_f32_16x16x32_bf16 v[6:9], v[168:171], v[212:215], v[6:9]
	v_mfma_f32_16x16x32_bf16 v[2:5], v[172:175], v[208:211], v[2:5]
	v_mfma_f32_16x16x32_bf16 v[2:5], v[176:179], v[212:215], v[2:5]
	s_setprio 0
	s_barrier
	s_add_i32 s72, 0, 0x18000
	s_add_i32 s73, 0, 0x1c000
	v_add_u32_e32 v160, s72, v1
	v_add_u32_e32 v176, s73, v1
	ds_read_b128 v[148:151], v160
	ds_read_b128 v[152:155], v160 offset:1024
	ds_read_b128 v[156:159], v160 offset:2048
	ds_read_b128 v[160:163], v160 offset:3072
	ds_read_b128 v[164:167], v176
	ds_read_b128 v[168:171], v176 offset:1024
	ds_read_b128 v[172:175], v176 offset:2048
	ds_read_b128 v[176:179], v176 offset:3072
	s_mov_b32 m0, s54
	v_lshl_add_u64 v[218:219], v[216:217], 0, s[12:13]
	ds_read_b128 v[180:183], v146 offset:32768
	ds_read_b128 v[188:191], v146 offset:33792
	ds_read_b128 v[192:195], v146 offset:34816
	ds_read_b128 v[196:199], v146 offset:35840
	ds_read_b128 v[200:203], v146 offset:36864
	ds_read_b128 v[204:207], v146 offset:37888
	ds_read_b128 v[208:211], v146 offset:38912
	ds_read_b128 v[212:215], v146 offset:39936
	global_load_lds_dwordx4 v[218:219], off
	v_lshl_add_u64 v[216:217], v[216:217], 0, s[14:15]
	s_mov_b32 m0, s55
	s_nop 0
	global_load_lds_dwordx4 v[216:217], off
	s_waitcnt vmcnt(8)
	s_waitcnt lgkmcnt(0)
	s_barrier
	s_setprio 1
	s_waitcnt lgkmcnt(0)
	v_mfma_f32_16x16x32_bf16 v[126:129], v[148:151], v[180:183], v[126:129]
	v_mfma_f32_16x16x32_bf16 v[126:129], v[152:155], v[188:191], v[126:129]
	v_mfma_f32_16x16x32_bf16 v[122:125], v[156:159], v[180:183], v[122:125]
	v_mfma_f32_16x16x32_bf16 v[122:125], v[160:163], v[188:191], v[122:125]
	v_mfma_f32_16x16x32_bf16 v[110:113], v[148:151], v[192:195], v[110:113]
	v_mfma_f32_16x16x32_bf16 v[110:113], v[152:155], v[196:199], v[110:113]
	v_mfma_f32_16x16x32_bf16 v[106:109], v[156:159], v[192:195], v[106:109]
	v_mfma_f32_16x16x32_bf16 v[106:109], v[160:163], v[196:199], v[106:109]
	v_mfma_f32_16x16x32_bf16 v[94:97], v[148:151], v[200:203], v[94:97]
	v_mfma_f32_16x16x32_bf16 v[94:97], v[152:155], v[204:207], v[94:97]
	v_mfma_f32_16x16x32_bf16 v[90:93], v[156:159], v[200:203], v[90:93]
	v_mfma_f32_16x16x32_bf16 v[90:93], v[160:163], v[204:207], v[90:93]
	v_mfma_f32_16x16x32_bf16 v[78:81], v[148:151], v[208:211], v[78:81]
	v_mfma_f32_16x16x32_bf16 v[78:81], v[152:155], v[212:215], v[78:81]
	v_mfma_f32_16x16x32_bf16 v[74:77], v[156:159], v[208:211], v[74:77]
	v_mfma_f32_16x16x32_bf16 v[74:77], v[160:163], v[212:215], v[74:77]
	s_setprio 0
	s_setprio 1
	v_mfma_f32_16x16x32_bf16 v[118:121], v[164:167], v[180:183], v[118:121]
	v_mfma_f32_16x16x32_bf16 v[118:121], v[168:171], v[188:191], v[118:121]
	v_mfma_f32_16x16x32_bf16 v[114:117], v[172:175], v[180:183], v[114:117]
	v_mfma_f32_16x16x32_bf16 v[114:117], v[176:179], v[188:191], v[114:117]
	v_mfma_f32_16x16x32_bf16 v[102:105], v[164:167], v[192:195], v[102:105]
	v_mfma_f32_16x16x32_bf16 v[102:105], v[168:171], v[196:199], v[102:105]
	v_mfma_f32_16x16x32_bf16 v[98:101], v[172:175], v[192:195], v[98:101]
	v_mfma_f32_16x16x32_bf16 v[98:101], v[176:179], v[196:199], v[98:101]
	v_mfma_f32_16x16x32_bf16 v[86:89], v[164:167], v[200:203], v[86:89]
	v_mfma_f32_16x16x32_bf16 v[86:89], v[168:171], v[204:207], v[86:89]
	v_mfma_f32_16x16x32_bf16 v[82:85], v[172:175], v[200:203], v[82:85]
	v_mfma_f32_16x16x32_bf16 v[82:85], v[176:179], v[204:207], v[82:85]
	v_mfma_f32_16x16x32_bf16 v[70:73], v[164:167], v[208:211], v[70:73]
	v_mfma_f32_16x16x32_bf16 v[70:73], v[168:171], v[212:215], v[70:73]
	v_mfma_f32_16x16x32_bf16 v[66:69], v[172:175], v[208:211], v[66:69]
	v_mfma_f32_16x16x32_bf16 v[66:69], v[176:179], v[212:215], v[66:69]
	s_setprio 0
	s_barrier
; __device__ __forceinline__ unsigned cvtpk(float lo, float hi) { f32x2 v = {lo, hi}; bf16x2_t b = __builtin_convertvector(v, bf16x2_t); return __builtin_bit_cast(unsigned, b); }
; #define PG8_STAGE(bufoff, gbase, voff) do { _Pragma("unroll") for (int _i = 0; _i < 2; ++_i) \
;         __builtin_amdgcn_global_load_lds((const unsigned*)((const char*)(gbase) + (size_t)_i * p##voff + (voff)), (LAS unsigned*)(lds + (bufoff) + ldsw + _i * 8192), 16, 0, 0); } while (0)
; #define PG8_LDA(dst, b, h) do { _Pragma("unroll") for (int m = 0; m < 4; ++m) _Pragma("unroll") for (int k = 0; k < 2; ++k) dst[m][k] = *(const LAS bf16x8*)(lds + PG8_SA(b, h) + aoff + m * 2048 + k * 1024); } while (0)
; #define PG8_WAIT_V(n) asm volatile("s_waitcnt vmcnt(" #n ")" ::: "memory")
; #define PG8_WAIT_L(n) asm volatile("s_waitcnt lgkmcnt(" #n ")" ::: "memory")
; #define PG8_BAR __builtin_amdgcn_s_barrier()
; #define PG8_SCHED __builtin_amdgcn_sched_barrier(0)
;     ...
;             PG8_LDA(At, 1, 1); PG8_STAGE(PG8_SB(1, 0), b3, voffB); PG8_STAGE(PG8_SB(1, 1), b3 + hstepB, voffB); PG8_STAGE(PG8_SA(1, 0), a3, voffA);
;             PG8_WAIT_V(8); PG8_WAIT_L(0); PG8_BAR; PG8_MMA(1, 0, At, B0); PG8_MMA(1, 1, At, B1); PG8_BAR; PG8_SCHED;
;     __device__ __forceinline__ void operator()(const Acc& acc, const Unit& u, int wr, int wc, int fr, int fq) const {
;     ...
;         const int rl = wr * 64 + fr, kt0 = u.pn * 4 + (wc >> 1), cl = (wc & 1) * 32 + 8 * fq;
; #pragma unroll
;         for (int ai = 0; ai < 2; ++ai)
; #pragma unroll
;             for (int m = 0; m < 4; ++m) { bf16_t* rp = O + (((size_t)u.pm * (DFF / 64) + kt0) * 256 + (rl + ai * 128 + m * 16)) * 64 + cl;
; #pragma unroll
;                 for (int bj = 0; bj < 2; ++bj) { f32x4 v0 = acc[ai][bj][m][0], v1 = acc[ai][bj][m][1];
; #pragma unroll
;                     for (int e = 0; e < 4; ++e) { const float a = fmaxf(v0[e], 0.f), b = fmaxf(v1[e], 0.f); v0[e] = a * a; v1[e] = b * b; }
;                     u32x4 w; w.x = cvtpk(v0[0], v0[1]); w.y = cvtpk(v0[2], v0[3]); w.z = cvtpk(v1[0], v1[1]); w.w = cvtpk(v1[2], v1[3]);
;                     *(u32x4*)(rp + (size_t)bj * 2 * 256 * 64) = w; } }
	s_add_i32 s72, s72, s50
	v_lshl_add_u64 v[216:217], v[184:185], 0, s[18:19]
	s_mov_b32 m0, s72
	ds_read_b128 v[180:183], v146 offset:49152
	ds_read_b128 v[188:191], v146 offset:50176
	ds_read_b128 v[192:195], v146 offset:51200
	ds_read_b128 v[196:199], v146 offset:52224
	ds_read_b128 v[200:203], v146 offset:53248
	ds_read_b128 v[204:207], v146 offset:54272
	ds_read_b128 v[208:211], v146 offset:55296
	ds_read_b128 v[212:215], v146 offset:56320
	global_load_lds_dwordx4 v[216:217], off
	v_lshl_add_u64 v[216:217], v[184:185], 0, s[20:21]
	s_add_i32 m0, s72, 0x2000
	s_add_i32 s72, s73, s50
	global_load_lds_dwordx4 v[216:217], off
	v_lshl_add_u64 v[216:217], v[184:185], 0, s[22:23]
	s_mov_b32 m0, s72
	v_lshl_add_u64 v[184:185], v[184:185], 0, s[24:25]
	global_load_lds_dwordx4 v[216:217], off
	s_add_i32 m0, s72, 0x2000
	s_nop 0
	global_load_lds_dwordx4 v[184:185], off
	v_lshl_add_u64 v[184:185], s[46:47], 0, v[130:131]
	s_mov_b32 m0, s58
	s_nop 0
	global_load_lds_dwordx4 v[184:185], off
	v_lshl_add_u64 v[184:185], v[184:185], 0, s[10:11]
	s_mov_b32 m0, s59
	s_nop 0
	global_load_lds_dwordx4 v[184:185], off
	s_waitcnt vmcnt(8)
	s_waitcnt lgkmcnt(0)
	s_barrier
	s_setprio 1
	s_waitcnt lgkmcnt(0)
	v_mfma_f32_16x16x32_bf16 v[62:65], v[148:151], v[180:183], v[62:65]
	v_mfma_f32_16x16x32_bf16 v[62:65], v[152:155], v[188:191], v[62:65]
	v_mfma_f32_16x16x32_bf16 v[58:61], v[156:159], v[180:183], v[58:61]
	v_mfma_f32_16x16x32_bf16 v[58:61], v[160:163], v[188:191], v[58:61]
	v_mfma_f32_16x16x32_bf16 v[46:49], v[148:151], v[192:195], v[46:49]
	v_mfma_f32_16x16x32_bf16 v[46:49], v[152:155], v[196:199], v[46:49]
	v_mfma_f32_16x16x32_bf16 v[42:45], v[156:159], v[192:195], v[42:45]
	v_mfma_f32_16x16x32_bf16 v[42:45], v[160:163], v[196:199], v[42:45]
	v_mfma_f32_16x16x32_bf16 v[30:33], v[148:151], v[200:203], v[30:33]
	v_mfma_f32_16x16x32_bf16 v[30:33], v[152:155], v[204:207], v[30:33]
	v_mfma_f32_16x16x32_bf16 v[26:29], v[156:159], v[200:203], v[26:29]
	v_mfma_f32_16x16x32_bf16 v[26:29], v[160:163], v[204:207], v[26:29]
	v_mfma_f32_16x16x32_bf16 v[14:17], v[148:151], v[208:211], v[14:17]
	v_mfma_f32_16x16x32_bf16 v[14:17], v[152:155], v[212:215], v[14:17]
	v_mfma_f32_16x16x32_bf16 v[10:13], v[156:159], v[208:211], v[10:13]
	v_mfma_f32_16x16x32_bf16 v[10:13], v[160:163], v[212:215], v[10:13]
	s_setprio 0
	s_setprio 1
	v_mfma_f32_16x16x32_bf16 v[54:57], v[164:167], v[180:183], v[54:57]
	v_mfma_f32_16x16x32_bf16 v[54:57], v[168:171], v[188:191], v[54:57]
	v_mfma_f32_16x16x32_bf16 v[50:53], v[172:175], v[180:183], v[50:53]
	v_mfma_f32_16x16x32_bf16 v[50:53], v[176:179], v[188:191], v[50:53]
	v_mfma_f32_16x16x32_bf16 v[38:41], v[164:167], v[192:195], v[38:41]
	v_mfma_f32_16x16x32_bf16 v[38:41], v[168:171], v[196:199], v[38:41]
	v_mfma_f32_16x16x32_bf16 v[34:37], v[172:175], v[192:195], v[34:37]
	v_mfma_f32_16x16x32_bf16 v[34:37], v[176:179], v[196:199], v[34:37]
	v_mfma_f32_16x16x32_bf16 v[22:25], v[164:167], v[200:203], v[22:25]
	v_mfma_f32_16x16x32_bf16 v[22:25], v[168:171], v[204:207], v[22:25]
	v_mfma_f32_16x16x32_bf16 v[18:21], v[172:175], v[200:203], v[18:21]
	v_mfma_f32_16x16x32_bf16 v[18:21], v[176:179], v[204:207], v[18:21]
	v_mfma_f32_16x16x32_bf16 v[6:9], v[164:167], v[208:211], v[6:9]
	v_mfma_f32_16x16x32_bf16 v[6:9], v[168:171], v[212:215], v[6:9]
	v_mfma_f32_16x16x32_bf16 v[2:5], v[172:175], v[208:211], v[2:5]
	v_mfma_f32_16x16x32_bf16 v[2:5], v[176:179], v[212:215], v[2:5]
	s_setprio 0
	s_barrier
	s_add_i32 s71, s71, 2
	s_add_u32 s69, s69, 0x100
	s_addc_u32 s70, s70, 0
	s_add_u32 s44, s44, 0x10000
	s_addc_u32 s45, s45, 0
	s_cmp_gt_u32 s71, 61
	s_cbranch_scc0 .LBB0_1206
	s_lshl_b32 s29, s41, 2
	s_or_b32 s42, s29, s61
	s_ashr_i32 s41, s40, 31
	s_ashr_i32 s43, s42, 31
	s_lshl_b64 s[40:41], s[40:41], 16
	s_lshl_b64 s[42:43], s[42:43], 8
	s_add_u32 s40, s42, s40
	v_lshrrev_b32_e32 v142, 1, v147
	s_addc_u32 s41, s43, s41
	v_and_b32_e32 v150, 56, v142
	v_lshl_add_u64 v[142:143], s[40:41], 0, v[134:135]
	v_max_f32_e32 v122, v122, v122
	v_max_f32_e32 v123, v123, v123
	v_lshlrev_b64 v[142:143], 7, v[142:143]
	v_max_f32_e32 v122, 0, v122
	v_max_f32_e32 v123, 0, v123
	v_lshl_add_u64 v[148:149], s[16:17], 0, v[142:143]
	v_add_lshl_u32 v142, v150, s62, 1
	v_pk_mul_f32 v[150:151], v[122:123], v[122:123]
	v_max_f32_e32 v123, v124, v124
	v_max_f32_e32 v126, v126, v126
	v_max_f32_e32 v127, v127, v127
	v_max_f32_e32 v122, v128, v128
	v_max_f32_e32 v124, 0, v123
	v_max_f32_e32 v123, v129, v129
	v_max_f32_e32 v125, v125, v125
	v_max_f32_e32 v126, 0, v126
	v_max_f32_e32 v127, 0, v127
	v_max_f32_e32 v122, 0, v122
	v_max_f32_e32 v123, 0, v123
	v_max_f32_e32 v125, 0, v125
	v_mov_b32_e32 v143, v135
	v_pk_mul_f32 v[126:127], v[126:127], v[126:127]
	v_pk_mul_f32 v[128:129], v[122:123], v[122:123]
	v_pk_mul_f32 v[152:153], v[124:125], v[124:125]
	v_max_f32_e32 v114, v114, v114
	v_max_f32_e32 v115, v115, v115
	v_lshl_add_u64 v[148:149], v[148:149], 0, v[142:143]
	v_cvt_pk_bf16_f32 v122, v126, v127
	v_cvt_pk_bf16_f32 v123, v128, v129
	v_cvt_pk_bf16_f32 v124, v150, v151
	v_cvt_pk_bf16_f32 v125, v152, v153
	v_max_f32_e32 v114, 0, v114
	v_max_f32_e32 v115, 0, v115
	global_store_dwordx4 v[148:149], v[122:125], off
	v_max_f32_e32 v118, v118, v118
	v_max_f32_e32 v119, v119, v119
	v_pk_mul_f32 v[122:123], v[114:115], v[114:115]
	v_max_f32_e32 v115, v116, v116
	v_max_f32_e32 v118, 0, v118
	v_max_f32_e32 v119, 0, v119
	v_max_f32_e32 v114, v120, v120
	v_max_f32_e32 v116, 0, v115
	v_max_f32_e32 v115, v121, v121
	v_max_f32_e32 v117, v117, v117
	v_pk_mul_f32 v[118:119], v[118:119], v[118:119]
	v_max_f32_e32 v114, 0, v114
	v_max_f32_e32 v115, 0, v115
	v_max_f32_e32 v117, 0, v117
; __device__ __forceinline__ unsigned cvtpk(float lo, float hi) { f32x2 v = {lo, hi}; bf16x2_t b = __builtin_convertvector(v, bf16x2_t); return __builtin_bit_cast(unsigned, b); }
;     __device__ __forceinline__ void operator()(const Acc& acc, const Unit& u, int wr, int wc, int fr, int fq) const {
;     ...
;             for (int m = 0; m < 4; ++m) { bf16_t* rp = O + (((size_t)u.pm * (DFF / 64) + kt0) * 256 + (rl + ai * 128 + m * 16)) * 64 + cl;
; #pragma unroll
;                 for (int bj = 0; bj < 2; ++bj) { f32x4 v0 = acc[ai][bj][m][0], v1 = acc[ai][bj][m][1];
; #pragma unroll
;                     for (int e = 0; e < 4; ++e) { const float a = fmaxf(v0[e], 0.f), b = fmaxf(v1[e], 0.f); v0[e] = a * a; v1[e] = b * b; }
;                     u32x4 w; w.x = cvtpk(v0[0], v0[1]); w.y = cvtpk(v0[2], v0[3]); w.z = cvtpk(v1[0], v1[1]); w.w = cvtpk(v1[2], v1[3]);
;                     *(u32x4*)(rp + (size_t)bj * 2 * 256 * 64) = w; } }
	v_pk_mul_f32 v[120:121], v[114:115], v[114:115]
	v_pk_mul_f32 v[124:125], v[116:117], v[116:117]
	v_cvt_pk_bf16_f32 v114, v118, v119
	v_add_co_u32_e32 v118, vcc, s57, v148
	v_max_f32_e32 v106, v106, v106
	v_max_f32_e32 v107, v107, v107
	v_cvt_pk_bf16_f32 v115, v120, v121
	v_cvt_pk_bf16_f32 v116, v122, v123
	v_cvt_pk_bf16_f32 v117, v124, v125
	v_addc_co_u32_e32 v119, vcc, 0, v149, vcc
	v_max_f32_e32 v106, 0, v106
	v_max_f32_e32 v107, 0, v107
	global_store_dwordx4 v[118:119], v[114:117], off
	v_max_f32_e32 v110, v110, v110
	v_max_f32_e32 v111, v111, v111
	v_or_b32_e32 v114, 16, v134
	v_mov_b32_e32 v115, v135
	v_pk_mul_f32 v[116:117], v[106:107], v[106:107]
	v_max_f32_e32 v107, v108, v108
	v_lshl_add_u64 v[114:115], s[40:41], 0, v[114:115]
	v_max_f32_e32 v106, v112, v112
	v_max_f32_e32 v108, 0, v107
	v_max_f32_e32 v107, v113, v113
	v_max_f32_e32 v109, v109, v109
	v_lshlrev_b64 v[114:115], 7, v[114:115]
	v_max_f32_e32 v110, 0, v110
	v_max_f32_e32 v111, 0, v111
	v_max_f32_e32 v106, 0, v106
	v_max_f32_e32 v107, 0, v107
	v_max_f32_e32 v109, 0, v109
	v_lshl_add_u64 v[114:115], s[16:17], 0, v[114:115]
	v_pk_mul_f32 v[110:111], v[110:111], v[110:111]
	v_pk_mul_f32 v[112:113], v[106:107], v[106:107]
	v_pk_mul_f32 v[118:119], v[108:109], v[108:109]
	v_max_f32_e32 v98, v98, v98
	v_max_f32_e32 v99, v99, v99
	v_lshl_add_u64 v[114:115], v[114:115], 0, v[142:143]
	v_cvt_pk_bf16_f32 v106, v110, v111
	v_cvt_pk_bf16_f32 v107, v112, v113
	v_cvt_pk_bf16_f32 v108, v116, v117
	v_cvt_pk_bf16_f32 v109, v118, v119
	v_max_f32_e32 v98, 0, v98
	v_max_f32_e32 v99, 0, v99
	global_store_dwordx4 v[114:115], v[106:109], off
	v_max_f32_e32 v102, v102, v102
	v_max_f32_e32 v103, v103, v103
	v_pk_mul_f32 v[106:107], v[98:99], v[98:99]
	v_max_f32_e32 v99, v100, v100
	v_max_f32_e32 v102, 0, v102
	v_max_f32_e32 v103, 0, v103
	v_max_f32_e32 v98, v104, v104
	v_max_f32_e32 v100, 0, v99
	v_max_f32_e32 v99, v105, v105
	v_max_f32_e32 v101, v101, v101
	v_pk_mul_f32 v[102:103], v[102:103], v[102:103]
	v_max_f32_e32 v98, 0, v98
	v_max_f32_e32 v99, 0, v99
	v_max_f32_e32 v101, 0, v101
	v_pk_mul_f32 v[104:105], v[98:99], v[98:99]
	v_pk_mul_f32 v[108:109], v[100:101], v[100:101]
	v_cvt_pk_bf16_f32 v98, v102, v103
	v_add_co_u32_e32 v102, vcc, s57, v114
	v_max_f32_e32 v90, v90, v90
	v_max_f32_e32 v91, v91, v91
	v_cvt_pk_bf16_f32 v99, v104, v105
	v_cvt_pk_bf16_f32 v100, v106, v107
	v_cvt_pk_bf16_f32 v101, v108, v109
	v_addc_co_u32_e32 v103, vcc, 0, v115, vcc
	v_max_f32_e32 v90, 0, v90
	v_max_f32_e32 v91, 0, v91
	global_store_dwordx4 v[102:103], v[98:101], off
	v_max_f32_e32 v94, v94, v94
	v_max_f32_e32 v95, v95, v95
	v_or_b32_e32 v98, 32, v134
	v_mov_b32_e32 v99, v135
	v_pk_mul_f32 v[100:101], v[90:91], v[90:91]
	v_max_f32_e32 v91, v92, v92
	v_lshl_add_u64 v[98:99], s[40:41], 0, v[98:99]
	v_max_f32_e32 v90, v96, v96
	v_max_f32_e32 v92, 0, v91
	v_max_f32_e32 v91, v97, v97
	v_max_f32_e32 v93, v93, v93
	v_lshlrev_b64 v[98:99], 7, v[98:99]
	v_max_f32_e32 v94, 0, v94
	v_max_f32_e32 v95, 0, v95
	v_max_f32_e32 v90, 0, v90
	v_max_f32_e32 v91, 0, v91
	v_max_f32_e32 v93, 0, v93
	v_lshl_add_u64 v[98:99], s[16:17], 0, v[98:99]
	v_pk_mul_f32 v[94:95], v[94:95], v[94:95]
	v_pk_mul_f32 v[96:97], v[90:91], v[90:91]
	v_pk_mul_f32 v[102:103], v[92:93], v[92:93]
	v_max_f32_e32 v82, v82, v82
	v_max_f32_e32 v83, v83, v83
	v_lshl_add_u64 v[98:99], v[98:99], 0, v[142:143]
	v_cvt_pk_bf16_f32 v90, v94, v95
	v_cvt_pk_bf16_f32 v91, v96, v97
	v_cvt_pk_bf16_f32 v92, v100, v101
	v_cvt_pk_bf16_f32 v93, v102, v103
	v_max_f32_e32 v82, 0, v82
	v_max_f32_e32 v83, 0, v83
	global_store_dwordx4 v[98:99], v[90:93], off
	v_max_f32_e32 v86, v86, v86
	v_max_f32_e32 v87, v87, v87
	v_pk_mul_f32 v[90:91], v[82:83], v[82:83]
	v_max_f32_e32 v83, v84, v84
	v_max_f32_e32 v86, 0, v86
	v_max_f32_e32 v87, 0, v87
	v_max_f32_e32 v82, v88, v88
	v_max_f32_e32 v84, 0, v83
	v_max_f32_e32 v83, v89, v89
	v_max_f32_e32 v85, v85, v85
	v_pk_mul_f32 v[86:87], v[86:87], v[86:87]
	v_max_f32_e32 v82, 0, v82
	v_max_f32_e32 v83, 0, v83
	v_max_f32_e32 v85, 0, v85
	v_pk_mul_f32 v[88:89], v[82:83], v[82:83]
	v_pk_mul_f32 v[92:93], v[84:85], v[84:85]
	v_cvt_pk_bf16_f32 v82, v86, v87
	v_add_co_u32_e32 v86, vcc, s57, v98
	v_max_f32_e32 v74, v74, v74
	v_max_f32_e32 v75, v75, v75
	v_cvt_pk_bf16_f32 v83, v88, v89
	v_cvt_pk_bf16_f32 v84, v90, v91
	v_cvt_pk_bf16_f32 v85, v92, v93
	v_addc_co_u32_e32 v87, vcc, 0, v99, vcc
	v_max_f32_e32 v74, 0, v74
	v_max_f32_e32 v75, 0, v75
	global_store_dwordx4 v[86:87], v[82:85], off
	v_max_f32_e32 v78, v78, v78
	v_max_f32_e32 v79, v79, v79
	v_or_b32_e32 v82, 48, v134
	v_mov_b32_e32 v83, v135
	v_pk_mul_f32 v[84:85], v[74:75], v[74:75]
	v_max_f32_e32 v75, v76, v76
	v_lshl_add_u64 v[82:83], s[40:41], 0, v[82:83]
	v_max_f32_e32 v74, v80, v80
	v_max_f32_e32 v76, 0, v75
	v_max_f32_e32 v75, v81, v81
	v_max_f32_e32 v77, v77, v77
	v_lshlrev_b64 v[82:83], 7, v[82:83]
	v_max_f32_e32 v78, 0, v78
	v_max_f32_e32 v79, 0, v79
	v_max_f32_e32 v74, 0, v74
	v_max_f32_e32 v75, 0, v75
	v_max_f32_e32 v77, 0, v77
	v_lshl_add_u64 v[82:83], s[16:17], 0, v[82:83]
	v_pk_mul_f32 v[78:79], v[78:79], v[78:79]
	v_pk_mul_f32 v[80:81], v[74:75], v[74:75]
	v_pk_mul_f32 v[86:87], v[76:77], v[76:77]
	v_max_f32_e32 v66, v66, v66
	v_max_f32_e32 v67, v67, v67
	v_lshl_add_u64 v[82:83], v[82:83], 0, v[142:143]
	v_cvt_pk_bf16_f32 v74, v78, v79
	v_cvt_pk_bf16_f32 v75, v80, v81
	v_cvt_pk_bf16_f32 v76, v84, v85
	v_cvt_pk_bf16_f32 v77, v86, v87
	v_max_f32_e32 v66, 0, v66
	v_max_f32_e32 v67, 0, v67
	global_store_dwordx4 v[82:83], v[74:77], off
	v_max_f32_e32 v70, v70, v70
	v_max_f32_e32 v71, v71, v71
	v_pk_mul_f32 v[74:75], v[66:67], v[66:67]
	v_max_f32_e32 v67, v68, v68
; __device__ __forceinline__ unsigned cvtpk(float lo, float hi) { f32x2 v = {lo, hi}; bf16x2_t b = __builtin_convertvector(v, bf16x2_t); return __builtin_bit_cast(unsigned, b); }
;     __device__ __forceinline__ void operator()(const Acc& acc, const Unit& u, int wr, int wc, int fr, int fq) const {
;     ...
;             for (int m = 0; m < 4; ++m) { bf16_t* rp = O + (((size_t)u.pm * (DFF / 64) + kt0) * 256 + (rl + ai * 128 + m * 16)) * 64 + cl;
; #pragma unroll
;                 for (int bj = 0; bj < 2; ++bj) { f32x4 v0 = acc[ai][bj][m][0], v1 = acc[ai][bj][m][1];
; #pragma unroll
;                     for (int e = 0; e < 4; ++e) { const float a = fmaxf(v0[e], 0.f), b = fmaxf(v1[e], 0.f); v0[e] = a * a; v1[e] = b * b; }
;                     u32x4 w; w.x = cvtpk(v0[0], v0[1]); w.y = cvtpk(v0[2], v0[3]); w.z = cvtpk(v1[0], v1[1]); w.w = cvtpk(v1[2], v1[3]);
;                     *(u32x4*)(rp + (size_t)bj * 2 * 256 * 64) = w; } }
	v_max_f32_e32 v70, 0, v70
	v_max_f32_e32 v71, 0, v71
	v_max_f32_e32 v66, v72, v72
	v_max_f32_e32 v68, 0, v67
	v_max_f32_e32 v67, v73, v73
	v_max_f32_e32 v69, v69, v69
	v_pk_mul_f32 v[70:71], v[70:71], v[70:71]
	v_max_f32_e32 v66, 0, v66
	v_max_f32_e32 v67, 0, v67
	v_max_f32_e32 v69, 0, v69
	v_pk_mul_f32 v[72:73], v[66:67], v[66:67]
	v_pk_mul_f32 v[76:77], v[68:69], v[68:69]
	v_cvt_pk_bf16_f32 v66, v70, v71
	v_add_co_u32_e32 v70, vcc, s57, v82
	v_max_f32_e32 v58, v58, v58
	v_max_f32_e32 v59, v59, v59
	v_cvt_pk_bf16_f32 v67, v72, v73
	v_cvt_pk_bf16_f32 v68, v74, v75
	v_cvt_pk_bf16_f32 v69, v76, v77
	v_addc_co_u32_e32 v71, vcc, 0, v83, vcc
	v_max_f32_e32 v58, 0, v58
	v_max_f32_e32 v59, 0, v59
	global_store_dwordx4 v[70:71], v[66:69], off
	v_max_f32_e32 v62, v62, v62
	v_max_f32_e32 v63, v63, v63
	v_add_u32_e32 v66, 0x80, v134
	v_mov_b32_e32 v67, v135
	v_pk_mul_f32 v[68:69], v[58:59], v[58:59]
	v_max_f32_e32 v59, v60, v60
	v_lshl_add_u64 v[66:67], s[40:41], 0, v[66:67]
	v_max_f32_e32 v58, v64, v64
	v_max_f32_e32 v60, 0, v59
	v_max_f32_e32 v59, v65, v65
	v_max_f32_e32 v61, v61, v61
	v_lshlrev_b64 v[66:67], 7, v[66:67]
	v_max_f32_e32 v62, 0, v62
	v_max_f32_e32 v63, 0, v63
	v_max_f32_e32 v58, 0, v58
	v_max_f32_e32 v59, 0, v59
	v_max_f32_e32 v61, 0, v61
	v_lshl_add_u64 v[66:67], s[16:17], 0, v[66:67]
	v_pk_mul_f32 v[62:63], v[62:63], v[62:63]
	v_pk_mul_f32 v[64:65], v[58:59], v[58:59]
	v_pk_mul_f32 v[70:71], v[60:61], v[60:61]
	v_max_f32_e32 v50, v50, v50
	v_max_f32_e32 v51, v51, v51
	v_lshl_add_u64 v[66:67], v[66:67], 0, v[142:143]
	v_cvt_pk_bf16_f32 v58, v62, v63
	v_cvt_pk_bf16_f32 v59, v64, v65
	v_cvt_pk_bf16_f32 v60, v68, v69
	v_cvt_pk_bf16_f32 v61, v70, v71
	v_max_f32_e32 v50, 0, v50
	v_max_f32_e32 v51, 0, v51
	global_store_dwordx4 v[66:67], v[58:61], off
	v_max_f32_e32 v54, v54, v54
	v_max_f32_e32 v55, v55, v55
	v_pk_mul_f32 v[58:59], v[50:51], v[50:51]
	v_max_f32_e32 v51, v52, v52
	v_max_f32_e32 v54, 0, v54
	v_max_f32_e32 v55, 0, v55
	v_max_f32_e32 v50, v56, v56
	v_max_f32_e32 v52, 0, v51
	v_max_f32_e32 v51, v57, v57
	v_max_f32_e32 v53, v53, v53
	v_pk_mul_f32 v[54:55], v[54:55], v[54:55]
	v_max_f32_e32 v50, 0, v50
	v_max_f32_e32 v51, 0, v51
	v_max_f32_e32 v53, 0, v53
	v_pk_mul_f32 v[56:57], v[50:51], v[50:51]
	v_pk_mul_f32 v[60:61], v[52:53], v[52:53]
	v_cvt_pk_bf16_f32 v50, v54, v55
	v_add_co_u32_e32 v54, vcc, s57, v66
	v_max_f32_e32 v42, v42, v42
	v_max_f32_e32 v43, v43, v43
	v_cvt_pk_bf16_f32 v51, v56, v57
	v_cvt_pk_bf16_f32 v52, v58, v59
	v_cvt_pk_bf16_f32 v53, v60, v61
	v_addc_co_u32_e32 v55, vcc, 0, v67, vcc
	v_max_f32_e32 v42, 0, v42
	v_max_f32_e32 v43, 0, v43
	global_store_dwordx4 v[54:55], v[50:53], off
	v_max_f32_e32 v46, v46, v46
	v_max_f32_e32 v47, v47, v47
	v_add_u32_e32 v50, 0x90, v134
	v_mov_b32_e32 v51, v135
	v_pk_mul_f32 v[52:53], v[42:43], v[42:43]
	v_max_f32_e32 v43, v44, v44
	v_lshl_add_u64 v[50:51], s[40:41], 0, v[50:51]
	v_max_f32_e32 v42, v48, v48
	v_max_f32_e32 v44, 0, v43
	v_max_f32_e32 v43, v49, v49
	v_max_f32_e32 v45, v45, v45
	v_lshlrev_b64 v[50:51], 7, v[50:51]
	v_max_f32_e32 v46, 0, v46
	v_max_f32_e32 v47, 0, v47
	v_max_f32_e32 v42, 0, v42
	v_max_f32_e32 v43, 0, v43
	v_max_f32_e32 v45, 0, v45
	v_lshl_add_u64 v[50:51], s[16:17], 0, v[50:51]
	v_pk_mul_f32 v[46:47], v[46:47], v[46:47]
	v_pk_mul_f32 v[48:49], v[42:43], v[42:43]
	v_pk_mul_f32 v[54:55], v[44:45], v[44:45]
	v_max_f32_e32 v34, v34, v34
	v_max_f32_e32 v35, v35, v35
	v_lshl_add_u64 v[50:51], v[50:51], 0, v[142:143]
	v_cvt_pk_bf16_f32 v42, v46, v47
	v_cvt_pk_bf16_f32 v43, v48, v49
	v_cvt_pk_bf16_f32 v44, v52, v53
	v_cvt_pk_bf16_f32 v45, v54, v55
	v_max_f32_e32 v34, 0, v34
	v_max_f32_e32 v35, 0, v35
	global_store_dwordx4 v[50:51], v[42:45], off
	v_max_f32_e32 v38, v38, v38
	v_max_f32_e32 v39, v39, v39
	v_pk_mul_f32 v[42:43], v[34:35], v[34:35]
	v_max_f32_e32 v35, v36, v36
	v_max_f32_e32 v38, 0, v38
	v_max_f32_e32 v39, 0, v39
	v_max_f32_e32 v34, v40, v40
	v_max_f32_e32 v36, 0, v35
	v_max_f32_e32 v35, v41, v41
	v_max_f32_e32 v37, v37, v37
	v_pk_mul_f32 v[38:39], v[38:39], v[38:39]
	v_max_f32_e32 v34, 0, v34
	v_max_f32_e32 v35, 0, v35
	v_max_f32_e32 v37, 0, v37
	v_pk_mul_f32 v[40:41], v[34:35], v[34:35]
	v_pk_mul_f32 v[44:45], v[36:37], v[36:37]
	v_cvt_pk_bf16_f32 v34, v38, v39
; __device__ __forceinline__ unsigned cvtpk(float lo, float hi) { f32x2 v = {lo, hi}; bf16x2_t b = __builtin_convertvector(v, bf16x2_t); return __builtin_bit_cast(unsigned, b); }
; #define PG8_WAIT_V(n) asm volatile("s_waitcnt vmcnt(" #n ")" ::: "memory")
; #define PG8_BAR __builtin_amdgcn_s_barrier()
;     ...
;         cur = nxt; cA = nA; cB = nB; ++ui;
;         if constexpr (ALIGN) { if (wr == 1) PG8_BAR; }
;     }
;     PG8_WAIT_V(0);
;     if constexpr (!ALIGN) { if (wr == 0) PG8_BAR; }
;     PG8_BAR;
;     __device__ __forceinline__ void operator()(const Acc& acc, const Unit& u, int wr, int wc, int fr, int fq) const {
;     ...
;             for (int m = 0; m < 4; ++m) { bf16_t* rp = O + (((size_t)u.pm * (DFF / 64) + kt0) * 256 + (rl + ai * 128 + m * 16)) * 64 + cl;
; #pragma unroll
;                 for (int bj = 0; bj < 2; ++bj) { f32x4 v0 = acc[ai][bj][m][0], v1 = acc[ai][bj][m][1];
; #pragma unroll
;                     for (int e = 0; e < 4; ++e) { const float a = fmaxf(v0[e], 0.f), b = fmaxf(v1[e], 0.f); v0[e] = a * a; v1[e] = b * b; }
;                     u32x4 w; w.x = cvtpk(v0[0], v0[1]); w.y = cvtpk(v0[2], v0[3]); w.z = cvtpk(v1[0], v1[1]); w.w = cvtpk(v1[2], v1[3]);
;                     *(u32x4*)(rp + (size_t)bj * 2 * 256 * 64) = w; } }
	v_add_co_u32_e32 v38, vcc, s57, v50
	v_max_f32_e32 v26, v26, v26
	v_max_f32_e32 v27, v27, v27
	v_cvt_pk_bf16_f32 v35, v40, v41
	v_cvt_pk_bf16_f32 v36, v42, v43
	v_cvt_pk_bf16_f32 v37, v44, v45
	v_addc_co_u32_e32 v39, vcc, 0, v51, vcc
	v_max_f32_e32 v26, 0, v26
	v_max_f32_e32 v27, 0, v27
	global_store_dwordx4 v[38:39], v[34:37], off
	v_max_f32_e32 v30, v30, v30
	v_max_f32_e32 v31, v31, v31
	v_add_u32_e32 v34, 0xa0, v134
	v_mov_b32_e32 v35, v135
	v_pk_mul_f32 v[36:37], v[26:27], v[26:27]
	v_max_f32_e32 v27, v28, v28
	v_lshl_add_u64 v[34:35], s[40:41], 0, v[34:35]
	v_max_f32_e32 v26, v32, v32
	v_max_f32_e32 v28, 0, v27
	v_max_f32_e32 v27, v33, v33
	v_max_f32_e32 v29, v29, v29
	v_lshlrev_b64 v[34:35], 7, v[34:35]
	v_max_f32_e32 v30, 0, v30
	v_max_f32_e32 v31, 0, v31
	v_max_f32_e32 v26, 0, v26
	v_max_f32_e32 v27, 0, v27
	v_max_f32_e32 v29, 0, v29
	v_lshl_add_u64 v[34:35], s[16:17], 0, v[34:35]
	v_pk_mul_f32 v[30:31], v[30:31], v[30:31]
	v_pk_mul_f32 v[32:33], v[26:27], v[26:27]
	v_pk_mul_f32 v[38:39], v[28:29], v[28:29]
	v_max_f32_e32 v18, v18, v18
	v_max_f32_e32 v19, v19, v19
	v_lshl_add_u64 v[34:35], v[34:35], 0, v[142:143]
	v_cvt_pk_bf16_f32 v26, v30, v31
	v_cvt_pk_bf16_f32 v27, v32, v33
	v_cvt_pk_bf16_f32 v28, v36, v37
	v_cvt_pk_bf16_f32 v29, v38, v39
	v_max_f32_e32 v18, 0, v18
	v_max_f32_e32 v19, 0, v19
	global_store_dwordx4 v[34:35], v[26:29], off
	v_max_f32_e32 v22, v22, v22
	v_max_f32_e32 v23, v23, v23
	v_pk_mul_f32 v[26:27], v[18:19], v[18:19]
	v_max_f32_e32 v19, v20, v20
	v_max_f32_e32 v22, 0, v22
	v_max_f32_e32 v23, 0, v23
	v_max_f32_e32 v18, v24, v24
	v_max_f32_e32 v20, 0, v19
	v_max_f32_e32 v19, v25, v25
	v_max_f32_e32 v21, v21, v21
	v_pk_mul_f32 v[22:23], v[22:23], v[22:23]
	v_max_f32_e32 v18, 0, v18
	v_max_f32_e32 v19, 0, v19
	v_max_f32_e32 v21, 0, v21
	v_pk_mul_f32 v[24:25], v[18:19], v[18:19]
	v_pk_mul_f32 v[28:29], v[20:21], v[20:21]
	v_cvt_pk_bf16_f32 v18, v22, v23
	v_add_co_u32_e32 v22, vcc, s57, v34
	v_max_f32_e32 v10, v10, v10
	v_max_f32_e32 v11, v11, v11
	v_cvt_pk_bf16_f32 v19, v24, v25
	v_cvt_pk_bf16_f32 v20, v26, v27
	v_cvt_pk_bf16_f32 v21, v28, v29
	v_addc_co_u32_e32 v23, vcc, 0, v35, vcc
	v_max_f32_e32 v10, 0, v10
	v_max_f32_e32 v11, 0, v11
	global_store_dwordx4 v[22:23], v[18:21], off
	v_max_f32_e32 v14, v14, v14
	v_max_f32_e32 v15, v15, v15
	v_add_u32_e32 v18, 0xb0, v134
	v_mov_b32_e32 v19, v135
	v_pk_mul_f32 v[20:21], v[10:11], v[10:11]
	v_max_f32_e32 v11, v12, v12
	v_lshl_add_u64 v[18:19], s[40:41], 0, v[18:19]
	v_max_f32_e32 v10, v16, v16
	v_max_f32_e32 v12, 0, v11
	v_max_f32_e32 v11, v17, v17
	v_max_f32_e32 v13, v13, v13
	v_lshlrev_b64 v[18:19], 7, v[18:19]
	v_max_f32_e32 v14, 0, v14
	v_max_f32_e32 v15, 0, v15
	v_max_f32_e32 v10, 0, v10
	v_max_f32_e32 v11, 0, v11
	v_max_f32_e32 v13, 0, v13
	v_lshl_add_u64 v[18:19], s[16:17], 0, v[18:19]
	v_pk_mul_f32 v[14:15], v[14:15], v[14:15]
	v_pk_mul_f32 v[16:17], v[10:11], v[10:11]
	v_pk_mul_f32 v[22:23], v[12:13], v[12:13]
	v_max_f32_e32 v2, v2, v2
	v_max_f32_e32 v3, v3, v3
	v_lshl_add_u64 v[18:19], v[18:19], 0, v[142:143]
	v_cvt_pk_bf16_f32 v10, v14, v15
	v_cvt_pk_bf16_f32 v11, v16, v17
	v_cvt_pk_bf16_f32 v12, v20, v21
	v_cvt_pk_bf16_f32 v13, v22, v23
	v_max_f32_e32 v2, 0, v2
	v_max_f32_e32 v3, 0, v3
	global_store_dwordx4 v[18:19], v[10:13], off
	v_max_f32_e32 v6, v6, v6
	v_max_f32_e32 v7, v7, v7
	v_pk_mul_f32 v[10:11], v[2:3], v[2:3]
	v_max_f32_e32 v3, v4, v4
	v_max_f32_e32 v6, 0, v6
	v_max_f32_e32 v7, 0, v7
	v_max_f32_e32 v2, v8, v8
	v_max_f32_e32 v4, 0, v3
	v_max_f32_e32 v3, v9, v9
	v_pk_mul_f32 v[6:7], v[6:7], v[6:7]
	v_max_f32_e32 v2, 0, v2
	v_max_f32_e32 v3, 0, v3
	v_max_f32_e32 v5, v5, v5
	v_max_f32_e32 v5, 0, v5
	v_pk_mul_f32 v[8:9], v[2:3], v[2:3]
	v_cvt_pk_bf16_f32 v2, v6, v7
	v_add_co_u32_e32 v6, vcc, 0x10000, v18
	v_pk_mul_f32 v[12:13], v[4:5], v[4:5]
	s_nop 0
	v_addc_co_u32_e32 v7, vcc, 0, v19, vcc
	v_cvt_pk_bf16_f32 v3, v8, v9
	v_cvt_pk_bf16_f32 v4, v10, v11
	v_cvt_pk_bf16_f32 v5, v12, v13
	s_and_b64 vcc, exec, s[2:3]
	s_mov_b32 s41, s28
	s_mov_b32 s40, s34
	s_mov_b64 s[44:45], s[38:39]
	s_mov_b64 s[42:43], s[36:37]
	global_store_dwordx4 v[6:7], v[2:5], off
	s_cbranch_vccz .LBB0_1199
	s_waitcnt vmcnt(0)
	s_cmpk_gt_u32 s33, 0xff
	s_cbranch_scc1 .LBB0_1210
	s_barrier

;     __device__ __forceinline__ size_t a_koff(int t) const { return (size_t)t * 128; }
;     __device__ __forceinline__ size_t a_koff(int t) const { return (size_t)t * 32768; }
; #define PG8_STAGE(bufoff, gbase, voff) do { _Pragma("unroll") for (int _i = 0; _i < 2; ++_i) \
;         __builtin_amdgcn_global_load_lds((const unsigned*)((const char*)(gbase) + (size_t)_i * p##voff + (voff)), (LAS unsigned*)(lds + (bufoff) + ldsw + _i * 8192), 16, 0, 0); } while (0)
; #define PG8_LDA(dst, b, h) do { _Pragma("unroll") for (int m = 0; m < 4; ++m) _Pragma("unroll") for (int k = 0; k < 2; ++k) dst[m][k] = *(const LAS bf16x8*)(lds + PG8_SA(b, h) + aoff + m * 2048 + k * 1024); } while (0)
; #define PG8_LDB(dst, b, h) do { _Pragma("unroll") for (int n = 0; n < 2; ++n) _Pragma("unroll") for (int k = 0; k < 2; ++k) dst[n][k] = *(const LAS bf16x8*)(lds + PG8_SB(b, h) + boff + n * 2048 + k * 1024); } while (0)
; #define PG8_WAIT_V(n) asm volatile("s_waitcnt vmcnt(" #n ")" ::: "memory")
; #define PG8_WAIT_L(n) asm volatile("s_waitcnt lgkmcnt(" #n ")" ::: "memory")
; #define PG8_BAR __builtin_amdgcn_s_barrier()
; #define PG8_SCHED __builtin_amdgcn_sched_barrier(0)
;     __device__ __forceinline__ size_t a_koff(int t) const { return ((size_t)(t >> 1) * 3072 + (size_t)(t & 1) * 64) * 2; }
;     __device__ __forceinline__ size_t a_koff(int t) const { return (size_t)t * 128; }
;     ...
;             const char* a1 = cA + g.a_koff(t + 1);
;             const char* a2 = last ? nA : cA + g.a_koff(t + 2); const char* b2 = last ? nB : cB + (size_t)(t + 2) * kstep;
;             const char* a3 = last ? nA + g.a_koff(1) : cA + g.a_koff(t + 3); const char* b3 = b2 + kstep;
;             PG8_LDB(B0, 0, 0); PG8_LDB(B1, 0, 1); PG8_SCHED; PG8_LDA(At, 0, 0); PG8_STAGE(PG8_SA(1, 1), a1 + hstepA, voffA);
;             PG8_WAIT_V(8); PG8_WAIT_L(0); PG8_BAR; PG8_MMA(0, 0, At, B0); PG8_MMA(0, 1, At, B1); PG8_BAR; PG8_SCHED;
;             PG8_LDA(At, 0, 1); PG8_STAGE(PG8_SB(0, 0), b2, voffB); PG8_STAGE(PG8_SB(0, 1), b2 + hstepB, voffB); PG8_STAGE(PG8_SA(0, 0), a2, voffA);
;             PG8_WAIT_V(8); PG8_WAIT_L(0); PG8_BAR; PG8_MMA(1, 0, At, B0); PG8_MMA(1, 1, At, B1); PG8_BAR; PG8_SCHED;
.LBB0_1281:
	ds_read_b128 v[142:145], v188
	ds_read_b128 v[146:149], v188 offset:1024
	ds_read_b128 v[150:153], v188 offset:2048
	ds_read_b128 v[154:157], v188 offset:3072
	ds_read_b128 v[158:161], v189
	ds_read_b128 v[162:165], v189 offset:1024
	ds_read_b128 v[166:169], v189 offset:2048
	ds_read_b128 v[170:173], v189 offset:3072
	s_add_u32 s50, s44, s48
	s_addc_u32 s51, s45, s49
	s_add_u32 s83, s50, 0x10000
	s_addc_u32 s86, s51, 0
	s_add_u32 s50, s50, 0x18000
	s_addc_u32 s51, s51, 0
	s_cmp_eq_u32 s48, 0x7f0000
	s_cselect_b32 s51, s79, s51
	s_cselect_b32 s50, s78, s50
	s_cselect_b32 s85, s35, s81
	s_cselect_b32 s84, s47, s80
	s_cselect_b32 s87, s37, s86
	s_cselect_b32 s86, s43, s83
	v_lshl_add_u64 v[212:213], v[140:141], 0, s[48:49]
	s_mov_b64 s[88:89], 0xc000
	v_lshl_add_u64 v[214:215], v[212:213], 0, s[88:89]
	s_add_i32 m0, s57, 0xc000
	s_mov_b64 s[88:89], 0xe000
	ds_read_b128 v[174:177], v190
	ds_read_b128 v[178:181], v190 offset:1024
	ds_read_b128 v[182:185], v190 offset:2048
	ds_read_b128 v[192:195], v190 offset:3072
	ds_read_b128 v[196:199], v190 offset:4096
	ds_read_b128 v[200:203], v190 offset:5120
	ds_read_b128 v[204:207], v190 offset:6144
	ds_read_b128 v[208:211], v190 offset:7168
	global_load_lds_dwordx4 v[214:215], off
	v_lshl_add_u64 v[212:213], v[212:213], 0, s[88:89]
	s_add_i32 m0, s57, 0xe000
	s_nop 0
	global_load_lds_dwordx4 v[212:213], off
	s_waitcnt vmcnt(8)
	s_waitcnt lgkmcnt(0)
	s_barrier
	s_setprio 1
	s_waitcnt lgkmcnt(0)
	v_mfma_f32_16x16x32_bf16 v[124:127], v[142:145], v[174:177], v[124:127]
	v_mfma_f32_16x16x32_bf16 v[124:127], v[146:149], v[178:181], v[124:127]
	v_mfma_f32_16x16x32_bf16 v[120:123], v[150:153], v[174:177], v[120:123]
	v_mfma_f32_16x16x32_bf16 v[120:123], v[154:157], v[178:181], v[120:123]
	v_mfma_f32_16x16x32_bf16 v[116:119], v[142:145], v[182:185], v[116:119]
	v_mfma_f32_16x16x32_bf16 v[116:119], v[146:149], v[192:195], v[116:119]
	v_mfma_f32_16x16x32_bf16 v[112:115], v[150:153], v[182:185], v[112:115]
	v_mfma_f32_16x16x32_bf16 v[112:115], v[154:157], v[192:195], v[112:115]
	v_mfma_f32_16x16x32_bf16 v[108:111], v[142:145], v[196:199], v[108:111]
	v_mfma_f32_16x16x32_bf16 v[108:111], v[146:149], v[200:203], v[108:111]
	v_mfma_f32_16x16x32_bf16 v[104:107], v[150:153], v[196:199], v[104:107]
	v_mfma_f32_16x16x32_bf16 v[104:107], v[154:157], v[200:203], v[104:107]
	v_mfma_f32_16x16x32_bf16 v[100:103], v[142:145], v[204:207], v[100:103]
	v_mfma_f32_16x16x32_bf16 v[100:103], v[146:149], v[208:211], v[100:103]
	v_mfma_f32_16x16x32_bf16 v[96:99], v[150:153], v[204:207], v[96:99]
	v_mfma_f32_16x16x32_bf16 v[96:99], v[154:157], v[208:211], v[96:99]
	s_setprio 0
	s_setprio 1
	v_mfma_f32_16x16x32_bf16 v[60:63], v[158:161], v[174:177], v[60:63]
	v_mfma_f32_16x16x32_bf16 v[60:63], v[162:165], v[178:181], v[60:63]
	v_mfma_f32_16x16x32_bf16 v[56:59], v[166:169], v[174:177], v[56:59]
	v_mfma_f32_16x16x32_bf16 v[56:59], v[170:173], v[178:181], v[56:59]
	v_mfma_f32_16x16x32_bf16 v[52:55], v[158:161], v[182:185], v[52:55]
	v_mfma_f32_16x16x32_bf16 v[52:55], v[162:165], v[192:195], v[52:55]
	v_mfma_f32_16x16x32_bf16 v[48:51], v[166:169], v[182:185], v[48:51]
	v_mfma_f32_16x16x32_bf16 v[48:51], v[170:173], v[192:195], v[48:51]
	v_mfma_f32_16x16x32_bf16 v[44:47], v[158:161], v[196:199], v[44:47]
	v_mfma_f32_16x16x32_bf16 v[44:47], v[162:165], v[200:203], v[44:47]
	v_mfma_f32_16x16x32_bf16 v[40:43], v[166:169], v[196:199], v[40:43]
	v_mfma_f32_16x16x32_bf16 v[40:43], v[170:173], v[200:203], v[40:43]
	v_mfma_f32_16x16x32_bf16 v[36:39], v[158:161], v[204:207], v[36:39]
	v_mfma_f32_16x16x32_bf16 v[36:39], v[162:165], v[208:211], v[36:39]
	v_mfma_f32_16x16x32_bf16 v[32:35], v[166:169], v[204:207], v[32:35]
	v_mfma_f32_16x16x32_bf16 v[32:35], v[170:173], v[208:211], v[32:35]
	s_setprio 0
	s_barrier
	s_add_i32 s83, s94, s56
	v_lshl_add_u64 v[212:213], s[84:85], 0, v[130:131]
	s_mov_b32 m0, s83
	ds_read_b128 v[174:177], v190 offset:16384
	ds_read_b128 v[178:181], v190 offset:17408
	ds_read_b128 v[182:185], v190 offset:18432
	ds_read_b128 v[192:195], v190 offset:19456
	ds_read_b128 v[196:199], v190 offset:20480
	ds_read_b128 v[200:203], v190 offset:21504
	ds_read_b128 v[204:207], v190 offset:22528
	ds_read_b128 v[208:211], v190 offset:23552
	global_load_lds_dwordx4 v[212:213], off
	v_lshl_add_u64 v[214:215], v[212:213], 0, s[4:5]
	s_add_i32 m0, s83, 0x2000
	s_add_i32 s83, s95, s56
	global_load_lds_dwordx4 v[214:215], off
	v_lshl_add_u64 v[214:215], v[212:213], 0, s[6:7]
	s_mov_b32 m0, s83
	s_nop 0
	global_load_lds_dwordx4 v[214:215], off
	v_lshl_add_u64 v[214:215], v[212:213], 0, s[8:9]
	s_add_i32 m0, s83, 0x2000
	s_nop 0
	global_load_lds_dwordx4 v[214:215], off
	v_lshl_add_u64 v[214:215], s[86:87], 0, v[128:129]
	s_mov_b32 m0, s57
	v_lshl_add_u64 v[216:217], v[214:215], 0, s[10:11]
	global_load_lds_dwordx4 v[214:215], off
	s_mov_b32 m0, s58
	s_nop 0
	global_load_lds_dwordx4 v[216:217], off
	s_waitcnt vmcnt(8)
	s_waitcnt lgkmcnt(0)
	s_barrier
; #define PG8_STAGE(bufoff, gbase, voff) do { _Pragma("unroll") for (int _i = 0; _i < 2; ++_i) \
;         __builtin_amdgcn_global_load_lds((const unsigned*)((const char*)(gbase) + (size_t)_i * p##voff + (voff)), (LAS unsigned*)(lds + (bufoff) + ldsw + _i * 8192), 16, 0, 0); } while (0)
; #define PG8_LDA(dst, b, h) do { _Pragma("unroll") for (int m = 0; m < 4; ++m) _Pragma("unroll") for (int k = 0; k < 2; ++k) dst[m][k] = *(const LAS bf16x8*)(lds + PG8_SA(b, h) + aoff + m * 2048 + k * 1024); } while (0)
; #define PG8_LDB(dst, b, h) do { _Pragma("unroll") for (int n = 0; n < 2; ++n) _Pragma("unroll") for (int k = 0; k < 2; ++k) dst[n][k] = *(const LAS bf16x8*)(lds + PG8_SB(b, h) + boff + n * 2048 + k * 1024); } while (0)
; #define PG8_WAIT_V(n) asm volatile("s_waitcnt vmcnt(" #n ")" ::: "memory")
; #define PG8_WAIT_L(n) asm volatile("s_waitcnt lgkmcnt(" #n ")" ::: "memory")
; #define PG8_BAR __builtin_amdgcn_s_barrier()
; #define PG8_SCHED __builtin_amdgcn_sched_barrier(0)
;     ...
;             PG8_WAIT_V(8); PG8_WAIT_L(0); PG8_BAR; PG8_MMA(1, 0, At, B0); PG8_MMA(1, 1, At, B1); PG8_BAR; PG8_SCHED;
;             PG8_LDB(B0, 1, 0); PG8_LDB(B1, 1, 1); PG8_SCHED; PG8_LDA(At, 1, 0); PG8_STAGE(PG8_SA(0, 1), a2 + hstepA, voffA);
;             PG8_WAIT_V(8); PG8_WAIT_L(0); PG8_BAR; PG8_MMA(0, 0, At, B0); PG8_MMA(0, 1, At, B1); PG8_BAR; PG8_SCHED;
;             PG8_LDA(At, 1, 1); PG8_STAGE(PG8_SB(1, 0), b3, voffB); PG8_STAGE(PG8_SB(1, 1), b3 + hstepB, voffB); PG8_STAGE(PG8_SA(1, 0), a3, voffA);
;             PG8_WAIT_V(8); PG8_WAIT_L(0); PG8_BAR; PG8_MMA(1, 0, At, B0); PG8_MMA(1, 1, At, B1); PG8_BAR; PG8_SCHED;
	s_setprio 1
	s_waitcnt lgkmcnt(0)
	v_mfma_f32_16x16x32_bf16 v[92:95], v[142:145], v[174:177], v[92:95]
	v_mfma_f32_16x16x32_bf16 v[92:95], v[146:149], v[178:181], v[92:95]
	v_mfma_f32_16x16x32_bf16 v[88:91], v[150:153], v[174:177], v[88:91]
	v_mfma_f32_16x16x32_bf16 v[88:91], v[154:157], v[178:181], v[88:91]
	v_mfma_f32_16x16x32_bf16 v[84:87], v[142:145], v[182:185], v[84:87]
	v_mfma_f32_16x16x32_bf16 v[84:87], v[146:149], v[192:195], v[84:87]
	v_mfma_f32_16x16x32_bf16 v[80:83], v[150:153], v[182:185], v[80:83]
	v_mfma_f32_16x16x32_bf16 v[80:83], v[154:157], v[192:195], v[80:83]
	v_mfma_f32_16x16x32_bf16 v[76:79], v[142:145], v[196:199], v[76:79]
	v_mfma_f32_16x16x32_bf16 v[76:79], v[146:149], v[200:203], v[76:79]
	v_mfma_f32_16x16x32_bf16 v[72:75], v[150:153], v[196:199], v[72:75]
	v_mfma_f32_16x16x32_bf16 v[72:75], v[154:157], v[200:203], v[72:75]
	v_mfma_f32_16x16x32_bf16 v[68:71], v[142:145], v[204:207], v[68:71]
	v_mfma_f32_16x16x32_bf16 v[68:71], v[146:149], v[208:211], v[68:71]
	v_mfma_f32_16x16x32_bf16 v[64:67], v[150:153], v[204:207], v[64:67]
	v_mfma_f32_16x16x32_bf16 v[64:67], v[154:157], v[208:211], v[64:67]
	s_setprio 0
	s_setprio 1
	v_mfma_f32_16x16x32_bf16 v[28:31], v[158:161], v[174:177], v[28:31]
	v_mfma_f32_16x16x32_bf16 v[28:31], v[162:165], v[178:181], v[28:31]
	v_mfma_f32_16x16x32_bf16 v[24:27], v[166:169], v[174:177], v[24:27]
	v_mfma_f32_16x16x32_bf16 v[24:27], v[170:173], v[178:181], v[24:27]
	v_mfma_f32_16x16x32_bf16 v[20:23], v[158:161], v[182:185], v[20:23]
	v_mfma_f32_16x16x32_bf16 v[20:23], v[162:165], v[192:195], v[20:23]
	v_mfma_f32_16x16x32_bf16 v[16:19], v[166:169], v[182:185], v[16:19]
	v_mfma_f32_16x16x32_bf16 v[16:19], v[170:173], v[192:195], v[16:19]
	v_mfma_f32_16x16x32_bf16 v[12:15], v[158:161], v[196:199], v[12:15]
	v_mfma_f32_16x16x32_bf16 v[12:15], v[162:165], v[200:203], v[12:15]
	v_mfma_f32_16x16x32_bf16 v[8:11], v[166:169], v[196:199], v[8:11]
	v_mfma_f32_16x16x32_bf16 v[8:11], v[170:173], v[200:203], v[8:11]
	v_mfma_f32_16x16x32_bf16 v[4:7], v[158:161], v[204:207], v[4:7]
	v_mfma_f32_16x16x32_bf16 v[4:7], v[162:165], v[208:211], v[4:7]
	v_mfma_f32_16x16x32_bf16 v[0:3], v[166:169], v[204:207], v[0:3]
	v_mfma_f32_16x16x32_bf16 v[0:3], v[170:173], v[208:211], v[0:3]
	s_setprio 0
	s_barrier
	s_add_i32 s83, 0, 0x18000
	v_add_u32_e32 v132, s83, v187
	s_add_i32 s84, 0, 0x1c000
	ds_read_b128 v[142:145], v132
	ds_read_b128 v[146:149], v132 offset:1024
	ds_read_b128 v[150:153], v132 offset:2048
	ds_read_b128 v[154:157], v132 offset:3072
	v_add_u32_e32 v132, s84, v187
	ds_read_b128 v[158:161], v132
	ds_read_b128 v[162:165], v132 offset:1024
	ds_read_b128 v[166:169], v132 offset:2048
	ds_read_b128 v[170:173], v132 offset:3072
	s_mov_b32 m0, s59
	v_lshl_add_u64 v[216:217], v[214:215], 0, s[12:13]
	ds_read_b128 v[174:177], v190 offset:32768
	ds_read_b128 v[178:181], v190 offset:33792
	ds_read_b128 v[182:185], v190 offset:34816
	ds_read_b128 v[192:195], v190 offset:35840
	ds_read_b128 v[196:199], v190 offset:36864
	ds_read_b128 v[200:203], v190 offset:37888
	ds_read_b128 v[204:207], v190 offset:38912
	ds_read_b128 v[208:211], v190 offset:39936
	global_load_lds_dwordx4 v[216:217], off
	v_lshl_add_u64 v[214:215], v[214:215], 0, s[14:15]
	s_mov_b32 m0, s60
	s_nop 0
	global_load_lds_dwordx4 v[214:215], off
	s_waitcnt vmcnt(8)
	s_waitcnt lgkmcnt(0)
	s_barrier
	s_setprio 1
	s_waitcnt lgkmcnt(0)
	v_mfma_f32_16x16x32_bf16 v[124:127], v[142:145], v[174:177], v[124:127]
	v_mfma_f32_16x16x32_bf16 v[124:127], v[146:149], v[178:181], v[124:127]
	v_mfma_f32_16x16x32_bf16 v[120:123], v[150:153], v[174:177], v[120:123]
	v_mfma_f32_16x16x32_bf16 v[120:123], v[154:157], v[178:181], v[120:123]
	v_mfma_f32_16x16x32_bf16 v[116:119], v[142:145], v[182:185], v[116:119]
	v_mfma_f32_16x16x32_bf16 v[116:119], v[146:149], v[192:195], v[116:119]
	v_mfma_f32_16x16x32_bf16 v[112:115], v[150:153], v[182:185], v[112:115]
	v_mfma_f32_16x16x32_bf16 v[112:115], v[154:157], v[192:195], v[112:115]
	v_mfma_f32_16x16x32_bf16 v[108:111], v[142:145], v[196:199], v[108:111]
	v_mfma_f32_16x16x32_bf16 v[108:111], v[146:149], v[200:203], v[108:111]
	v_mfma_f32_16x16x32_bf16 v[104:107], v[150:153], v[196:199], v[104:107]
	v_mfma_f32_16x16x32_bf16 v[104:107], v[154:157], v[200:203], v[104:107]
	v_mfma_f32_16x16x32_bf16 v[100:103], v[142:145], v[204:207], v[100:103]
	v_mfma_f32_16x16x32_bf16 v[100:103], v[146:149], v[208:211], v[100:103]
	v_mfma_f32_16x16x32_bf16 v[96:99], v[150:153], v[204:207], v[96:99]
	v_mfma_f32_16x16x32_bf16 v[96:99], v[154:157], v[208:211], v[96:99]
	s_setprio 0
	s_setprio 1
	v_mfma_f32_16x16x32_bf16 v[60:63], v[158:161], v[174:177], v[60:63]
	v_mfma_f32_16x16x32_bf16 v[60:63], v[162:165], v[178:181], v[60:63]
	v_mfma_f32_16x16x32_bf16 v[56:59], v[166:169], v[174:177], v[56:59]
	v_mfma_f32_16x16x32_bf16 v[56:59], v[170:173], v[178:181], v[56:59]
	v_mfma_f32_16x16x32_bf16 v[52:55], v[158:161], v[182:185], v[52:55]
	v_mfma_f32_16x16x32_bf16 v[52:55], v[162:165], v[192:195], v[52:55]
	v_mfma_f32_16x16x32_bf16 v[48:51], v[166:169], v[182:185], v[48:51]
	v_mfma_f32_16x16x32_bf16 v[48:51], v[170:173], v[192:195], v[48:51]
	v_mfma_f32_16x16x32_bf16 v[44:47], v[158:161], v[196:199], v[44:47]
	v_mfma_f32_16x16x32_bf16 v[44:47], v[162:165], v[200:203], v[44:47]
	v_mfma_f32_16x16x32_bf16 v[40:43], v[166:169], v[196:199], v[40:43]
	v_mfma_f32_16x16x32_bf16 v[40:43], v[170:173], v[200:203], v[40:43]
	v_mfma_f32_16x16x32_bf16 v[36:39], v[158:161], v[204:207], v[36:39]
	v_mfma_f32_16x16x32_bf16 v[36:39], v[162:165], v[208:211], v[36:39]
	v_mfma_f32_16x16x32_bf16 v[32:35], v[166:169], v[204:207], v[32:35]
	v_mfma_f32_16x16x32_bf16 v[32:35], v[170:173], v[208:211], v[32:35]
	s_setprio 0
	s_barrier
; #define PG8_STAGE(bufoff, gbase, voff) do { _Pragma("unroll") for (int _i = 0; _i < 2; ++_i) \
;         __builtin_amdgcn_global_load_lds((const unsigned*)((const char*)(gbase) + (size_t)_i * p##voff + (voff)), (LAS unsigned*)(lds + (bufoff) + ldsw + _i * 8192), 16, 0, 0); } while (0)
; #define PG8_LDA(dst, b, h) do { _Pragma("unroll") for (int m = 0; m < 4; ++m) _Pragma("unroll") for (int k = 0; k < 2; ++k) dst[m][k] = *(const LAS bf16x8*)(lds + PG8_SA(b, h) + aoff + m * 2048 + k * 1024); } while (0)
; #define PG8_WAIT_V(n) asm volatile("s_waitcnt vmcnt(" #n ")" ::: "memory")
; #define PG8_WAIT_L(n) asm volatile("s_waitcnt lgkmcnt(" #n ")" ::: "memory")
; #define PG8_BAR __builtin_amdgcn_s_barrier()
; #define PG8_SCHED __builtin_amdgcn_sched_barrier(0)
;     ...
;             PG8_LDA(At, 1, 1); PG8_STAGE(PG8_SB(1, 0), b3, voffB); PG8_STAGE(PG8_SB(1, 1), b3 + hstepB, voffB); PG8_STAGE(PG8_SA(1, 0), a3, voffA);
;             PG8_WAIT_V(8); PG8_WAIT_L(0); PG8_BAR; PG8_MMA(1, 0, At, B0); PG8_MMA(1, 1, At, B1); PG8_BAR; PG8_SCHED;
;     __device__ __forceinline__ void operator()(const Acc& acc, const Unit& u, int wr, int wc, int fr, int fq) const {
;     ...
;         const int rowb = u.pm * 256 + wr * 64 + fr, col0 = u.pn * 256 + wc * 32 + 8 * fq; const int b = (u.pm * 256) / S;
;         const size_t yb = (((size_t)u.pm * 16 + u.pn) * 256 + (wr * 64 + fr)) * 256 + wc * 32 + 8 * fq;
; #pragma unroll
;         for (int bj = 0; bj < 2; ++bj) {
;             f32x4 gm[2], G[2], Bc[2];
; #pragma unroll
;             for (int n = 0; n < 2; ++n) { const int c = col0 + bj * 128 + n * 4; gm[n] = *(const f32x4*)(gate + (size_t)b * NADA + c) + 1.0f; G[n] = *(const f32x4*)(lg + c) * ALPHA; Bc[n] = *(const f32x4*)(lb + c) * ALPHA; }
; #pragma unroll
;             for (int hf = 0; hf < 2; ++hf) {
;                 u32x4 yv[4]; f32x2 st[4];
; #pragma unroll
;                 for (int m = 0; m < 4; ++m) { const int row = rowb + hf * 128 + m * 16; yv[m] = *(const u32x4*)(y1 + yb + (size_t)(hf * 128 + m * 16) * 256 + bj * 128); st[m] = *(const f32x2*)(stats + (size_t)row * 2); }
	s_add_i32 s83, s83, s56
	v_lshl_add_u64 v[214:215], v[212:213], 0, s[20:21]
	s_mov_b32 m0, s83
	ds_read_b128 v[174:177], v190 offset:49152
	ds_read_b128 v[178:181], v190 offset:50176
	ds_read_b128 v[182:185], v190 offset:51200
	ds_read_b128 v[192:195], v190 offset:52224
	ds_read_b128 v[196:199], v190 offset:53248
	ds_read_b128 v[200:203], v190 offset:54272
	ds_read_b128 v[204:207], v190 offset:55296
	ds_read_b128 v[208:211], v190 offset:56320
	global_load_lds_dwordx4 v[214:215], off
	v_lshl_add_u64 v[214:215], v[212:213], 0, s[22:23]
	s_add_i32 m0, s83, 0x2000
	s_add_i32 s83, s84, s56
	global_load_lds_dwordx4 v[214:215], off
	v_lshl_add_u64 v[214:215], v[212:213], 0, s[24:25]
	s_mov_b32 m0, s83
	v_lshl_add_u64 v[212:213], v[212:213], 0, s[26:27]
	global_load_lds_dwordx4 v[214:215], off
	s_add_i32 m0, s83, 0x2000
	s_nop 0
	global_load_lds_dwordx4 v[212:213], off
	v_lshl_add_u64 v[212:213], s[50:51], 0, v[128:129]
	s_mov_b32 m0, s71
	s_nop 0
	global_load_lds_dwordx4 v[212:213], off
	v_lshl_add_u64 v[212:213], v[212:213], 0, s[10:11]
	s_mov_b32 m0, s72
	s_nop 0
	global_load_lds_dwordx4 v[212:213], off
	s_waitcnt vmcnt(8)
	s_waitcnt lgkmcnt(0)
	s_barrier
	s_setprio 1
	s_waitcnt lgkmcnt(0)
	v_mfma_f32_16x16x32_bf16 v[92:95], v[142:145], v[174:177], v[92:95]
	v_mfma_f32_16x16x32_bf16 v[92:95], v[146:149], v[178:181], v[92:95]
	v_mfma_f32_16x16x32_bf16 v[88:91], v[150:153], v[174:177], v[88:91]
	v_mfma_f32_16x16x32_bf16 v[88:91], v[154:157], v[178:181], v[88:91]
	v_mfma_f32_16x16x32_bf16 v[84:87], v[142:145], v[182:185], v[84:87]
	v_mfma_f32_16x16x32_bf16 v[84:87], v[146:149], v[192:195], v[84:87]
	v_mfma_f32_16x16x32_bf16 v[80:83], v[150:153], v[182:185], v[80:83]
	v_mfma_f32_16x16x32_bf16 v[80:83], v[154:157], v[192:195], v[80:83]
	v_mfma_f32_16x16x32_bf16 v[76:79], v[142:145], v[196:199], v[76:79]
	v_mfma_f32_16x16x32_bf16 v[76:79], v[146:149], v[200:203], v[76:79]
	v_mfma_f32_16x16x32_bf16 v[72:75], v[150:153], v[196:199], v[72:75]
	v_mfma_f32_16x16x32_bf16 v[72:75], v[154:157], v[200:203], v[72:75]
	v_mfma_f32_16x16x32_bf16 v[68:71], v[142:145], v[204:207], v[68:71]
	v_mfma_f32_16x16x32_bf16 v[68:71], v[146:149], v[208:211], v[68:71]
	v_mfma_f32_16x16x32_bf16 v[64:67], v[150:153], v[204:207], v[64:67]
	v_mfma_f32_16x16x32_bf16 v[64:67], v[154:157], v[208:211], v[64:67]
	s_setprio 0
	s_setprio 1
	v_mfma_f32_16x16x32_bf16 v[28:31], v[158:161], v[174:177], v[28:31]
	v_mfma_f32_16x16x32_bf16 v[28:31], v[162:165], v[178:181], v[28:31]
	v_mfma_f32_16x16x32_bf16 v[24:27], v[166:169], v[174:177], v[24:27]
	v_mfma_f32_16x16x32_bf16 v[24:27], v[170:173], v[178:181], v[24:27]
	v_mfma_f32_16x16x32_bf16 v[20:23], v[158:161], v[182:185], v[20:23]
	v_mfma_f32_16x16x32_bf16 v[20:23], v[162:165], v[192:195], v[20:23]
	v_mfma_f32_16x16x32_bf16 v[16:19], v[166:169], v[182:185], v[16:19]
	v_mfma_f32_16x16x32_bf16 v[16:19], v[170:173], v[192:195], v[16:19]
	v_mfma_f32_16x16x32_bf16 v[12:15], v[158:161], v[196:199], v[12:15]
	v_mfma_f32_16x16x32_bf16 v[12:15], v[162:165], v[200:203], v[12:15]
	v_mfma_f32_16x16x32_bf16 v[8:11], v[166:169], v[196:199], v[8:11]
	v_mfma_f32_16x16x32_bf16 v[8:11], v[170:173], v[200:203], v[8:11]
	v_mfma_f32_16x16x32_bf16 v[4:7], v[158:161], v[204:207], v[4:7]
	v_mfma_f32_16x16x32_bf16 v[4:7], v[162:165], v[208:211], v[4:7]
	v_mfma_f32_16x16x32_bf16 v[0:3], v[166:169], v[204:207], v[0:3]
	v_mfma_f32_16x16x32_bf16 v[0:3], v[170:173], v[208:211], v[0:3]
	s_setprio 0
	s_barrier
	s_add_i32 s82, s82, 2
	s_add_u32 s80, s80, 0x100
	s_addc_u32 s81, s81, 0
	s_add_u32 s48, s48, 0x10000
	s_addc_u32 s49, s49, 0
	s_cmpk_gt_u32 s82, 0xfd
	s_cbranch_scc0 .LBB0_1281
	s_lshl_b32 s37, s46, 8
	v_lshrrev_b32_e32 v132, 1, v191
	s_or_b32 s37, s37, s74
	v_and_b32_e32 v141, 56, v132
	s_ashr_i32 s43, s42, 31
	v_add_u32_e32 v140, s37, v141
	s_lshr_b32 s37, s43, 28
	s_lshl_b32 s35, s42, 8
	s_add_i32 s37, s42, s37
	s_ashr_i32 s47, s46, 31
	s_add_i32 s35, s35, s73
	s_ashr_i32 s37, s37, 4
	s_lshl_b64 s[42:43], s[42:43], 12
	s_lshl_b64 s[44:45], s[46:47], 8
	v_and_b32_e32 v150, 15, v191
	s_add_u32 s42, s42, s44
	s_addc_u32 s43, s43, s45
	v_or_b32_e32 v132, s73, v150
	v_lshl_add_u64 v[148:149], s[42:43], 0, v[132:133]
	s_mul_hi_i32 s43, s37, 0x18000
	s_mul_i32 s37, s37, 0x18000
	v_add_u32_e32 v132, s74, v141
	v_ashrrev_i32_e32 v141, 31, v140
	v_readlane_b32 s76, v245, 10
	s_add_u32 s42, s69, s37
	v_lshlrev_b64 v[220:221], 9, v[148:149]
	v_or_b32_e32 v154, s35, v150
	v_lshlrev_b64 v[140:141], 2, v[140:141]
	v_readlane_b32 s78, v245, 12
	v_readlane_b32 s79, v245, 13
	v_readlane_b32 s80, v245, 14
	v_readlane_b32 s81, v245, 15
	s_addc_u32 s43, s70, s43
	v_lshl_or_b32 v220, v132, 1, v220
	v_ashrrev_i32_e32 v155, 31, v154
	v_lshl_add_u64 v[142:143], s[78:79], 0, v[140:141]
	v_lshl_add_u64 v[144:145], s[80:81], 0, v[140:141]
	v_lshl_add_u64 v[146:147], s[42:43], 0, v[140:141]
	v_lshl_add_u64 v[148:149], s[16:17], 0, v[220:221]
	v_lshl_add_u64 v[140:141], v[154:155], 3, s[18:19]
	global_load_dwordx4 v[164:167], v[142:143], off offset:16
	global_load_dwordx4 v[168:171], v[142:143], off
	global_load_dwordx4 v[182:185], v[144:145], off offset:16
	global_load_dwordx4 v[192:195], v[144:145], off
	global_load_dwordx4 v[196:199], v[146:147], off offset:16
	global_load_dwordx4 v[200:203], v[146:147], off
	global_load_dwordx4 v[204:207], v[148:149], off
	global_load_dwordx2 v[222:223], v[140:141], off
	v_or_b32_e32 v152, 16, v154
	v_add_co_u32_e32 v150, vcc, s66, v148
	v_ashrrev_i32_e32 v153, 31, v152
	s_nop 0
	v_addc_co_u32_e32 v151, vcc, 0, v149, vcc
	v_lshl_add_u64 v[152:153], v[152:153], 3, s[18:19]
	global_load_dwordx4 v[208:211], v[150:151], off
	global_load_dwordx2 v[224:225], v[152:153], off
	v_add_co_u32_e32 v158, vcc, s67, v148
	v_or_b32_e32 v156, 32, v154
	s_nop 0
	v_addc_co_u32_e32 v159, vcc, 0, v149, vcc
	v_or_b32_e32 v154, 48, v154
	v_ashrrev_i32_e32 v157, 31, v156
	global_load_dwordx4 v[212:215], v[158:159], off
	v_ashrrev_i32_e32 v155, 31, v154
	v_lshl_add_u64 v[160:161], v[156:157], 3, s[18:19]
	v_add_co_u32_e32 v156, vcc, s68, v148
	v_lshl_add_u64 v[154:155], v[154:155], 3, s[18:19]
	s_nop 0
	v_addc_co_u32_e32 v157, vcc, 0, v149, vcc
	global_load_dwordx2 v[226:227], v[160:161], off
	global_load_dwordx4 v[216:219], v[156:157], off
	global_load_dwordx2 v[228:229], v[154:155], off
	v_readlane_b32 s42, v245, 61
	v_readlane_b32 s43, v245, 62
	s_mov_b32 s46, s34
	s_mov_b64 s[48:49], s[40:41]
	s_mov_b64 s[44:45], s[38:39]
	v_readlane_b32 s77, v245, 11
	v_readlane_b32 s82, v245, 16
	v_readlane_b32 s83, v245, 17
	v_readlane_b32 s84, v245, 18
	v_readlane_b32 s85, v245, 19
	v_readlane_b32 s86, v245, 20
	v_readlane_b32 s87, v245, 21
	v_readlane_b32 s88, v245, 22
	v_readlane_b32 s89, v245, 23
	v_readlane_b32 s90, v245, 24
	v_readlane_b32 s91, v245, 25
	s_waitcnt vmcnt(0)
; __device__ __forceinline__ u32x4 pack8f(f32x4 lo, f32x4 hi) { u32x4 w; w.x = cvtpk(lo[0], lo[1]); w.y = cvtpk(lo[2], lo[3]); w.z = cvtpk(hi[0], hi[1]); w.w = cvtpk(hi[2], hi[3]); return w; }
;     __device__ __forceinline__ void operator()(const Acc& acc, const Unit& u, int wr, int wc, int fr, int fq) const {
;     ...
;         for (int bj = 0; bj < 2; ++bj) {
;             f32x4 gm[2], G[2], Bc[2];
; #pragma unroll
;             for (int n = 0; n < 2; ++n) { const int c = col0 + bj * 128 + n * 4; gm[n] = *(const f32x4*)(gate + (size_t)b * NADA + c) + 1.0f; G[n] = *(const f32x4*)(lg + c) * ALPHA; Bc[n] = *(const f32x4*)(lb + c) * ALPHA; }
; #pragma unroll
;             for (int hf = 0; hf < 2; ++hf) {
;                 u32x4 yv[4]; f32x2 st[4];
; #pragma unroll
;                 for (int m = 0; m < 4; ++m) { const int row = rowb + hf * 128 + m * 16; yv[m] = *(const u32x4*)(y1 + yb + (size_t)(hf * 128 + m * 16) * 256 + bj * 128); st[m] = *(const f32x2*)(stats + (size_t)row * 2); }
; #pragma unroll
;                 for (int m = 0; m < 4; ++m) { const int row = rowb + hf * 128 + m * 16;
;                     f32x4 lo, hi; unpack8(yv[m], lo, hi); const float r = st[m][1], mr = st[m][0] * r;
;                     lo = (lo * r - mr) * G[0] + Bc[0] + gm[0] * acc[hf][bj][m][0]; hi = (hi * r - mr) * G[1] + Bc[1] + gm[1] * acc[hf][bj][m][1];
;                     *(u32x4*)(y2 + yb + (size_t)(hf * 128 + m * 16) * 256 + bj * 128) = pack8f(lo, hi); }
	v_pk_mul_f32 v[162:163], v[166:167], s[28:29] op_sel_hi:[1,0]
	v_pk_mul_f32 v[166:167], v[184:185], s[28:29] op_sel_hi:[1,0]
	v_pk_mul_f32 v[178:179], v[194:195], s[28:29] op_sel_hi:[1,0]
	v_pk_mul_f32 v[180:181], v[192:193], s[28:29] op_sel_hi:[1,0]
	v_pk_add_f32 v[184:185], v[200:201], 1.0 op_sel_hi:[1,0]
	v_lshlrev_b32_e32 v192, 16, v204
	v_and_b32_e32 v193, 0xffff0000, v204
	v_lshlrev_b32_e32 v194, 16, v205
	v_and_b32_e32 v195, 0xffff0000, v205
	v_pk_mul_f32 v[200:201], v[222:223], v[222:223] op_sel:[0,1] op_sel_hi:[1,0]
	v_pk_mul_f32 v[174:175], v[170:171], s[28:29] op_sel_hi:[1,0]
	v_pk_mul_f32 v[176:177], v[168:169], s[28:29] op_sel_hi:[1,0]
	v_pk_fma_f32 v[192:193], v[222:223], v[192:193], v[200:201] op_sel:[1,0,0] op_sel_hi:[1,1,0] neg_lo:[0,0,1] neg_hi:[0,0,1]
	v_pk_fma_f32 v[194:195], v[222:223], v[194:195], v[200:201] op_sel:[1,0,0] op_sel_hi:[1,1,0] neg_lo:[0,0,1] neg_hi:[0,0,1]
	v_pk_mul_f32 v[172:173], v[182:183], s[28:29] op_sel_hi:[1,0]
	v_pk_add_f32 v[182:183], v[202:203], 1.0 op_sel_hi:[1,0]
	v_pk_add_f32 v[168:169], v[198:199], 1.0 op_sel_hi:[1,0]
	v_pk_add_f32 v[170:171], v[196:197], 1.0 op_sel_hi:[1,0]
	v_lshlrev_b32_e32 v196, 16, v206
	v_and_b32_e32 v197, 0xffff0000, v206
	v_lshlrev_b32_e32 v198, 16, v207
	v_and_b32_e32 v199, 0xffff0000, v207
	v_pk_fma_f32 v[194:195], v[174:175], v[194:195], v[178:179]
	v_pk_fma_f32 v[192:193], v[176:177], v[192:193], v[180:181]
	v_pk_mul_f32 v[164:165], v[164:165], s[28:29] op_sel_hi:[1,0]
	v_pk_fma_f32 v[126:127], v[126:127], v[182:183], v[194:195]
	v_pk_fma_f32 v[124:125], v[124:125], v[184:185], v[192:193]
	v_pk_fma_f32 v[192:193], v[222:223], v[196:197], v[200:201] op_sel:[1,0,0] op_sel_hi:[1,1,0] neg_lo:[0,0,1] neg_hi:[0,0,1]
	v_pk_fma_f32 v[194:195], v[222:223], v[198:199], v[200:201] op_sel:[1,0,0] op_sel_hi:[1,1,0] neg_lo:[0,0,1] neg_hi:[0,0,1]
	v_pk_fma_f32 v[192:193], v[164:165], v[192:193], v[172:173]
	v_pk_fma_f32 v[194:195], v[162:163], v[194:195], v[166:167]
	v_pk_fma_f32 v[120:121], v[120:121], v[170:171], v[192:193]
	v_pk_fma_f32 v[194:195], v[122:123], v[168:169], v[194:195]
	v_cvt_pk_bf16_f32 v122, v124, v125
	v_cvt_pk_bf16_f32 v123, v126, v127
	v_cvt_pk_bf16_f32 v124, v120, v121
	v_cvt_pk_bf16_f32 v125, v194, v195
	v_lshl_add_u64 v[120:121], s[42:43], 0, v[220:221]
	global_store_dwordx4 v[120:121], v[122:125], off
	v_pk_mul_f32 v[194:195], v[224:225], v[224:225] op_sel:[0,1] op_sel_hi:[1,0]
	v_lshlrev_b32_e32 v126, 16, v210
	v_lshlrev_b32_e32 v124, 16, v209
	v_and_b32_e32 v125, 0xffff0000, v209
	v_lshlrev_b32_e32 v122, 16, v208
	v_and_b32_e32 v123, 0xffff0000, v208
	v_pk_fma_f32 v[124:125], v[224:225], v[124:125], v[194:195] op_sel:[1,0,0] op_sel_hi:[1,1,0] neg_lo:[0,0,1] neg_hi:[0,0,1]
	v_and_b32_e32 v127, 0xffff0000, v210
	v_pk_fma_f32 v[122:123], v[224:225], v[122:123], v[194:195] op_sel:[1,0,0] op_sel_hi:[1,1,0] neg_lo:[0,0,1] neg_hi:[0,0,1]
	v_pk_fma_f32 v[124:125], v[174:175], v[124:125], v[178:179]
	v_lshlrev_b32_e32 v192, 16, v211
	v_and_b32_e32 v193, 0xffff0000, v211
	v_pk_fma_f32 v[122:123], v[176:177], v[122:123], v[180:181]
	v_pk_fma_f32 v[118:119], v[118:119], v[182:183], v[124:125]
	v_pk_fma_f32 v[124:125], v[224:225], v[126:127], v[194:195] op_sel:[1,0,0] op_sel_hi:[1,1,0] neg_lo:[0,0,1] neg_hi:[0,0,1]
	v_pk_fma_f32 v[116:117], v[116:117], v[184:185], v[122:123]
	v_pk_fma_f32 v[122:123], v[224:225], v[192:193], v[194:195] op_sel:[1,0,0] op_sel_hi:[1,1,0] neg_lo:[0,0,1] neg_hi:[0,0,1]
	v_pk_fma_f32 v[124:125], v[164:165], v[124:125], v[172:173]
	v_pk_fma_f32 v[122:123], v[162:163], v[122:123], v[166:167]
	v_pk_fma_f32 v[112:113], v[112:113], v[170:171], v[124:125]
	v_pk_fma_f32 v[122:123], v[114:115], v[168:169], v[122:123]
	v_cvt_pk_bf16_f32 v114, v116, v117
	v_cvt_pk_bf16_f32 v116, v112, v113
	v_add_co_u32_e32 v112, vcc, s66, v120
	v_cvt_pk_bf16_f32 v115, v118, v119
	v_cvt_pk_bf16_f32 v117, v122, v123
	v_addc_co_u32_e32 v113, vcc, 0, v121, vcc
	global_store_dwordx4 v[112:113], v[114:117], off
	v_pk_mul_f32 v[124:125], v[226:227], v[226:227] op_sel:[0,1] op_sel_hi:[1,0]
	v_lshlrev_b32_e32 v118, 16, v214
	v_lshlrev_b32_e32 v116, 16, v213
	v_and_b32_e32 v117, 0xffff0000, v213
	v_lshlrev_b32_e32 v114, 16, v212
	v_and_b32_e32 v115, 0xffff0000, v212
	v_pk_fma_f32 v[116:117], v[226:227], v[116:117], v[124:125] op_sel:[1,0,0] op_sel_hi:[1,1,0] neg_lo:[0,0,1] neg_hi:[0,0,1]
	v_and_b32_e32 v119, 0xffff0000, v214
	v_pk_fma_f32 v[114:115], v[226:227], v[114:115], v[124:125] op_sel:[1,0,0] op_sel_hi:[1,1,0] neg_lo:[0,0,1] neg_hi:[0,0,1]
	v_pk_fma_f32 v[116:117], v[174:175], v[116:117], v[178:179]
	v_lshlrev_b32_e32 v122, 16, v215
	v_and_b32_e32 v123, 0xffff0000, v215
	v_pk_fma_f32 v[114:115], v[176:177], v[114:115], v[180:181]
	v_pk_fma_f32 v[110:111], v[110:111], v[182:183], v[116:117]
	v_pk_fma_f32 v[116:117], v[226:227], v[118:119], v[124:125] op_sel:[1,0,0] op_sel_hi:[1,1,0] neg_lo:[0,0,1] neg_hi:[0,0,1]
	v_pk_fma_f32 v[108:109], v[108:109], v[184:185], v[114:115]
	v_pk_fma_f32 v[114:115], v[226:227], v[122:123], v[124:125] op_sel:[1,0,0] op_sel_hi:[1,1,0] neg_lo:[0,0,1] neg_hi:[0,0,1]
	v_pk_fma_f32 v[116:117], v[164:165], v[116:117], v[172:173]
	v_pk_fma_f32 v[114:115], v[162:163], v[114:115], v[166:167]
	v_pk_fma_f32 v[104:105], v[104:105], v[170:171], v[116:117]
	v_pk_fma_f32 v[114:115], v[106:107], v[168:169], v[114:115]
	v_cvt_pk_bf16_f32 v106, v108, v109
	v_cvt_pk_bf16_f32 v108, v104, v105
	v_add_co_u32_e32 v104, vcc, s67, v120
	v_cvt_pk_bf16_f32 v107, v110, v111
	v_cvt_pk_bf16_f32 v109, v114, v115
	v_addc_co_u32_e32 v105, vcc, 0, v121, vcc
	global_store_dwordx4 v[104:105], v[106:109], off
	v_pk_mul_f32 v[116:117], v[228:229], v[228:229] op_sel:[0,1] op_sel_hi:[1,0]
; __device__ __forceinline__ u32x4 pack8f(f32x4 lo, f32x4 hi) { u32x4 w; w.x = cvtpk(lo[0], lo[1]); w.y = cvtpk(lo[2], lo[3]); w.z = cvtpk(hi[0], hi[1]); w.w = cvtpk(hi[2], hi[3]); return w; }
;     __device__ __forceinline__ void operator()(const Acc& acc, const Unit& u, int wr, int wc, int fr, int fq) const {
;     ...
;                 for (int m = 0; m < 4; ++m) { const int row = rowb + hf * 128 + m * 16; yv[m] = *(const u32x4*)(y1 + yb + (size_t)(hf * 128 + m * 16) * 256 + bj * 128); st[m] = *(const f32x2*)(stats + (size_t)row * 2); }
; #pragma unroll
;                 for (int m = 0; m < 4; ++m) { const int row = rowb + hf * 128 + m * 16;
;                     f32x4 lo, hi; unpack8(yv[m], lo, hi); const float r = st[m][1], mr = st[m][0] * r;
;                     lo = (lo * r - mr) * G[0] + Bc[0] + gm[0] * acc[hf][bj][m][0]; hi = (hi * r - mr) * G[1] + Bc[1] + gm[1] * acc[hf][bj][m][1];
;                     *(u32x4*)(y2 + yb + (size_t)(hf * 128 + m * 16) * 256 + bj * 128) = pack8f(lo, hi); }
;                 asm volatile("" ::: "memory");
	v_lshlrev_b32_e32 v110, 16, v218
	v_lshlrev_b32_e32 v108, 16, v217
	v_and_b32_e32 v109, 0xffff0000, v217
	v_lshlrev_b32_e32 v106, 16, v216
	v_and_b32_e32 v107, 0xffff0000, v216
	v_pk_fma_f32 v[108:109], v[228:229], v[108:109], v[116:117] op_sel:[1,0,0] op_sel_hi:[1,1,0] neg_lo:[0,0,1] neg_hi:[0,0,1]
	v_and_b32_e32 v111, 0xffff0000, v218
	v_pk_fma_f32 v[106:107], v[228:229], v[106:107], v[116:117] op_sel:[1,0,0] op_sel_hi:[1,1,0] neg_lo:[0,0,1] neg_hi:[0,0,1]
	v_pk_fma_f32 v[108:109], v[174:175], v[108:109], v[178:179]
	v_lshlrev_b32_e32 v114, 16, v219
	v_and_b32_e32 v115, 0xffff0000, v219
	v_pk_fma_f32 v[106:107], v[176:177], v[106:107], v[180:181]
	v_pk_fma_f32 v[102:103], v[102:103], v[182:183], v[108:109]
	v_pk_fma_f32 v[108:109], v[228:229], v[110:111], v[116:117] op_sel:[1,0,0] op_sel_hi:[1,1,0] neg_lo:[0,0,1] neg_hi:[0,0,1]
	v_pk_fma_f32 v[100:101], v[100:101], v[184:185], v[106:107]
	v_pk_fma_f32 v[106:107], v[228:229], v[114:115], v[116:117] op_sel:[1,0,0] op_sel_hi:[1,1,0] neg_lo:[0,0,1] neg_hi:[0,0,1]
	v_pk_fma_f32 v[108:109], v[164:165], v[108:109], v[172:173]
	v_pk_fma_f32 v[106:107], v[162:163], v[106:107], v[166:167]
	v_pk_fma_f32 v[96:97], v[96:97], v[170:171], v[108:109]
	v_pk_fma_f32 v[106:107], v[98:99], v[168:169], v[106:107]
	v_cvt_pk_bf16_f32 v98, v100, v101
	v_cvt_pk_bf16_f32 v100, v96, v97
	v_add_co_u32_e32 v96, vcc, s68, v120
	v_cvt_pk_bf16_f32 v99, v102, v103
	v_cvt_pk_bf16_f32 v101, v106, v107
	v_addc_co_u32_e32 v97, vcc, 0, v121, vcc
	global_store_dwordx4 v[96:97], v[98:101], off
	s_mov_b32 s42, s36
	s_nop 0
	v_add_co_u32_e32 v98, vcc, s62, v148
	s_nop 1
	v_addc_co_u32_e32 v99, vcc, 0, v149, vcc
	global_load_dwordx4 v[108:111], v[98:99], off
	global_load_dwordx2 v[118:119], v[140:141], off offset:1024
	v_add_co_u32_e32 v100, vcc, s63, v148
	s_waitcnt vmcnt(1)
	v_lshlrev_b32_e32 v200, 16, v108
	v_addc_co_u32_e32 v101, vcc, 0, v149, vcc
	global_load_dwordx4 v[114:117], v[100:101], off
	global_load_dwordx2 v[126:127], v[140:141], off offset:1152
	v_add_co_u32_e32 v102, vcc, s64, v148
	v_and_b32_e32 v201, 0xffff0000, v108
	s_nop 0
	v_addc_co_u32_e32 v103, vcc, 0, v149, vcc
	global_load_dwordx4 v[122:125], v[102:103], off
	global_load_dwordx2 v[196:197], v[140:141], off offset:1280
	v_add_co_u32_e32 v106, vcc, s65, v148
	v_lshlrev_b32_e32 v108, 16, v109
	s_nop 0
	v_addc_co_u32_e32 v107, vcc, 0, v149, vcc
	global_load_dwordx4 v[192:195], v[106:107], off
	global_load_dwordx2 v[198:199], v[140:141], off offset:1408
	v_and_b32_e32 v109, 0xffff0000, v109
	s_waitcnt vmcnt(6)
	v_pk_mul_f32 v[204:205], v[118:119], v[118:119] op_sel:[0,1] op_sel_hi:[1,0]
	v_lshlrev_b32_e32 v202, 16, v110
	v_pk_fma_f32 v[108:109], v[118:119], v[108:109], v[204:205] op_sel:[1,0,0] op_sel_hi:[1,1,0] neg_lo:[0,0,1] neg_hi:[0,0,1]
	v_and_b32_e32 v203, 0xffff0000, v110
	v_lshlrev_b32_e32 v110, 16, v111
	v_and_b32_e32 v111, 0xffff0000, v111
	v_pk_fma_f32 v[108:109], v[174:175], v[108:109], v[178:179]
	v_pk_fma_f32 v[200:201], v[118:119], v[200:201], v[204:205] op_sel:[1,0,0] op_sel_hi:[1,1,0] neg_lo:[0,0,1] neg_hi:[0,0,1]
	v_pk_fma_f32 v[94:95], v[94:95], v[182:183], v[108:109]
	v_pk_fma_f32 v[108:109], v[118:119], v[110:111], v[204:205] op_sel:[1,0,0] op_sel_hi:[1,1,0] neg_lo:[0,0,1] neg_hi:[0,0,1]
	v_pk_fma_f32 v[110:111], v[118:119], v[202:203], v[204:205] op_sel:[1,0,0] op_sel_hi:[1,1,0] neg_lo:[0,0,1] neg_hi:[0,0,1]
	v_pk_fma_f32 v[200:201], v[176:177], v[200:201], v[180:181]
	v_pk_fma_f32 v[110:111], v[164:165], v[110:111], v[172:173]
	v_pk_fma_f32 v[92:93], v[92:93], v[184:185], v[200:201]
	v_pk_fma_f32 v[108:109], v[162:163], v[108:109], v[166:167]
	v_pk_fma_f32 v[88:89], v[88:89], v[170:171], v[110:111]
	v_pk_fma_f32 v[108:109], v[90:91], v[168:169], v[108:109]
	v_cvt_pk_bf16_f32 v90, v92, v93
	v_cvt_pk_bf16_f32 v92, v88, v89
	v_add_co_u32_e32 v88, vcc, s62, v120
	v_cvt_pk_bf16_f32 v91, v94, v95
	v_cvt_pk_bf16_f32 v93, v108, v109
	v_addc_co_u32_e32 v89, vcc, 0, v121, vcc
	global_store_dwordx4 v[88:89], v[90:93], off
	s_waitcnt vmcnt(6)
	v_lshlrev_b32_e32 v94, 16, v116
	v_lshlrev_b32_e32 v92, 16, v115
	v_and_b32_e32 v93, 0xffff0000, v115
	s_waitcnt vmcnt(5)
	v_pk_mul_f32 v[110:111], v[126:127], v[126:127] op_sel:[0,1] op_sel_hi:[1,0]
	v_lshlrev_b32_e32 v90, 16, v114
	v_and_b32_e32 v91, 0xffff0000, v114
	v_pk_fma_f32 v[92:93], v[126:127], v[92:93], v[110:111] op_sel:[1,0,0] op_sel_hi:[1,1,0] neg_lo:[0,0,1] neg_hi:[0,0,1]
	v_and_b32_e32 v95, 0xffff0000, v116
	v_pk_fma_f32 v[90:91], v[126:127], v[90:91], v[110:111] op_sel:[1,0,0] op_sel_hi:[1,1,0] neg_lo:[0,0,1] neg_hi:[0,0,1]
	v_pk_fma_f32 v[92:93], v[174:175], v[92:93], v[178:179]
	v_lshlrev_b32_e32 v108, 16, v117
	v_and_b32_e32 v109, 0xffff0000, v117
	v_pk_fma_f32 v[90:91], v[176:177], v[90:91], v[180:181]
	v_pk_fma_f32 v[86:87], v[86:87], v[182:183], v[92:93]
	v_pk_fma_f32 v[92:93], v[126:127], v[94:95], v[110:111] op_sel:[1,0,0] op_sel_hi:[1,1,0] neg_lo:[0,0,1] neg_hi:[0,0,1]
	v_pk_fma_f32 v[84:85], v[84:85], v[184:185], v[90:91]
	v_pk_fma_f32 v[90:91], v[126:127], v[108:109], v[110:111] op_sel:[1,0,0] op_sel_hi:[1,1,0] neg_lo:[0,0,1] neg_hi:[0,0,1]
	v_pk_fma_f32 v[92:93], v[164:165], v[92:93], v[172:173]
	v_pk_fma_f32 v[90:91], v[162:163], v[90:91], v[166:167]
	v_pk_fma_f32 v[80:81], v[80:81], v[170:171], v[92:93]
	v_pk_fma_f32 v[90:91], v[82:83], v[168:169], v[90:91]
	v_cvt_pk_bf16_f32 v82, v84, v85
	v_cvt_pk_bf16_f32 v84, v80, v81
	v_add_co_u32_e32 v80, vcc, s63, v120
	v_cvt_pk_bf16_f32 v83, v86, v87
	v_cvt_pk_bf16_f32 v85, v90, v91
	v_addc_co_u32_e32 v81, vcc, 0, v121, vcc
	global_store_dwordx4 v[80:81], v[82:85], off
	s_waitcnt vmcnt(4)
; __device__ __forceinline__ u32x4 pack8f(f32x4 lo, f32x4 hi) { u32x4 w; w.x = cvtpk(lo[0], lo[1]); w.y = cvtpk(lo[2], lo[3]); w.z = cvtpk(hi[0], hi[1]); w.w = cvtpk(hi[2], hi[3]); return w; }
;     __device__ __forceinline__ void operator()(const Acc& acc, const Unit& u, int wr, int wc, int fr, int fq) const {
;     ...
;         for (int bj = 0; bj < 2; ++bj) {
;             f32x4 gm[2], G[2], Bc[2];
; #pragma unroll
;             for (int n = 0; n < 2; ++n) { const int c = col0 + bj * 128 + n * 4; gm[n] = *(const f32x4*)(gate + (size_t)b * NADA + c) + 1.0f; G[n] = *(const f32x4*)(lg + c) * ALPHA; Bc[n] = *(const f32x4*)(lb + c) * ALPHA; }
; #pragma unroll
;             for (int hf = 0; hf < 2; ++hf) {
;                 u32x4 yv[4]; f32x2 st[4];
; #pragma unroll
;                 for (int m = 0; m < 4; ++m) { const int row = rowb + hf * 128 + m * 16; yv[m] = *(const u32x4*)(y1 + yb + (size_t)(hf * 128 + m * 16) * 256 + bj * 128); st[m] = *(const f32x2*)(stats + (size_t)row * 2); }
; #pragma unroll
;                 for (int m = 0; m < 4; ++m) { const int row = rowb + hf * 128 + m * 16;
;                     f32x4 lo, hi; unpack8(yv[m], lo, hi); const float r = st[m][1], mr = st[m][0] * r;
;                     lo = (lo * r - mr) * G[0] + Bc[0] + gm[0] * acc[hf][bj][m][0]; hi = (hi * r - mr) * G[1] + Bc[1] + gm[1] * acc[hf][bj][m][1];
;                     *(u32x4*)(y2 + yb + (size_t)(hf * 128 + m * 16) * 256 + bj * 128) = pack8f(lo, hi); }
;                 asm volatile("" ::: "memory");
	v_pk_mul_f32 v[92:93], v[196:197], v[196:197] op_sel:[0,1] op_sel_hi:[1,0]
	v_lshlrev_b32_e32 v86, 16, v124
	v_lshlrev_b32_e32 v84, 16, v123
	v_and_b32_e32 v85, 0xffff0000, v123
	v_lshlrev_b32_e32 v82, 16, v122
	v_and_b32_e32 v83, 0xffff0000, v122
	v_pk_fma_f32 v[84:85], v[196:197], v[84:85], v[92:93] op_sel:[1,0,0] op_sel_hi:[1,1,0] neg_lo:[0,0,1] neg_hi:[0,0,1]
	v_and_b32_e32 v87, 0xffff0000, v124
	v_pk_fma_f32 v[82:83], v[196:197], v[82:83], v[92:93] op_sel:[1,0,0] op_sel_hi:[1,1,0] neg_lo:[0,0,1] neg_hi:[0,0,1]
	v_pk_fma_f32 v[84:85], v[174:175], v[84:85], v[178:179]
	v_lshlrev_b32_e32 v90, 16, v125
	v_and_b32_e32 v91, 0xffff0000, v125
	v_pk_fma_f32 v[82:83], v[176:177], v[82:83], v[180:181]
	v_pk_fma_f32 v[78:79], v[78:79], v[182:183], v[84:85]
	v_pk_fma_f32 v[84:85], v[196:197], v[86:87], v[92:93] op_sel:[1,0,0] op_sel_hi:[1,1,0] neg_lo:[0,0,1] neg_hi:[0,0,1]
	v_pk_fma_f32 v[76:77], v[76:77], v[184:185], v[82:83]
	v_pk_fma_f32 v[82:83], v[196:197], v[90:91], v[92:93] op_sel:[1,0,0] op_sel_hi:[1,1,0] neg_lo:[0,0,1] neg_hi:[0,0,1]
	v_pk_fma_f32 v[84:85], v[164:165], v[84:85], v[172:173]
	v_pk_fma_f32 v[82:83], v[162:163], v[82:83], v[166:167]
	v_pk_fma_f32 v[72:73], v[72:73], v[170:171], v[84:85]
	v_pk_fma_f32 v[82:83], v[74:75], v[168:169], v[82:83]
	v_cvt_pk_bf16_f32 v74, v76, v77
	v_cvt_pk_bf16_f32 v76, v72, v73
	v_add_co_u32_e32 v72, vcc, s64, v120
	v_cvt_pk_bf16_f32 v75, v78, v79
	v_cvt_pk_bf16_f32 v77, v82, v83
	v_addc_co_u32_e32 v73, vcc, 0, v121, vcc
	global_store_dwordx4 v[72:73], v[74:77], off
	s_waitcnt vmcnt(3)
	v_pk_mul_f32 v[84:85], v[198:199], v[198:199] op_sel:[0,1] op_sel_hi:[1,0]
	v_lshlrev_b32_e32 v78, 16, v194
	v_lshlrev_b32_e32 v76, 16, v193
	v_and_b32_e32 v77, 0xffff0000, v193
	v_lshlrev_b32_e32 v74, 16, v192
	v_and_b32_e32 v75, 0xffff0000, v192
	v_pk_fma_f32 v[76:77], v[198:199], v[76:77], v[84:85] op_sel:[1,0,0] op_sel_hi:[1,1,0] neg_lo:[0,0,1] neg_hi:[0,0,1]
	v_and_b32_e32 v79, 0xffff0000, v194
	v_pk_fma_f32 v[74:75], v[198:199], v[74:75], v[84:85] op_sel:[1,0,0] op_sel_hi:[1,1,0] neg_lo:[0,0,1] neg_hi:[0,0,1]
	v_pk_fma_f32 v[76:77], v[174:175], v[76:77], v[178:179]
	v_lshlrev_b32_e32 v82, 16, v195
	v_and_b32_e32 v83, 0xffff0000, v195
	v_pk_fma_f32 v[74:75], v[176:177], v[74:75], v[180:181]
	v_pk_fma_f32 v[70:71], v[70:71], v[182:183], v[76:77]
	v_pk_fma_f32 v[76:77], v[198:199], v[78:79], v[84:85] op_sel:[1,0,0] op_sel_hi:[1,1,0] neg_lo:[0,0,1] neg_hi:[0,0,1]
	v_pk_fma_f32 v[68:69], v[68:69], v[184:185], v[74:75]
	v_pk_fma_f32 v[74:75], v[198:199], v[82:83], v[84:85] op_sel:[1,0,0] op_sel_hi:[1,1,0] neg_lo:[0,0,1] neg_hi:[0,0,1]
	v_pk_fma_f32 v[76:77], v[164:165], v[76:77], v[172:173]
	v_pk_fma_f32 v[74:75], v[162:163], v[74:75], v[166:167]
	v_pk_fma_f32 v[64:65], v[64:65], v[170:171], v[76:77]
	v_pk_fma_f32 v[74:75], v[66:67], v[168:169], v[74:75]
	v_cvt_pk_bf16_f32 v66, v68, v69
	v_cvt_pk_bf16_f32 v68, v64, v65
	v_add_co_u32_e32 v64, vcc, s65, v120
	v_cvt_pk_bf16_f32 v67, v70, v71
	v_cvt_pk_bf16_f32 v69, v74, v75
	v_addc_co_u32_e32 v65, vcc, 0, v121, vcc
	global_store_dwordx4 v[64:65], v[66:69], off
	global_load_dwordx4 v[66:69], v[146:147], off offset:512
	global_load_dwordx4 v[82:85], v[142:143], off offset:512
	global_load_dwordx4 v[108:111], v[144:145], off offset:512
	global_load_dwordx4 v[114:117], v[146:147], off offset:528
	global_load_dwordx4 v[122:125], v[142:143], off offset:528
	s_nop 0
	global_load_dwordx4 v[142:145], v[144:145], off offset:528
	s_nop 0
	global_load_dwordx4 v[146:149], v[148:149], off offset:256
	s_nop 0
	global_load_dwordx2 v[118:119], v[140:141], off
	global_load_dwordx4 v[162:165], v[150:151], off offset:256
	global_load_dwordx2 v[126:127], v[152:153], off
	s_nop 0
	global_load_dwordx4 v[150:153], v[158:159], off offset:256
	s_nop 0
	global_load_dwordx2 v[158:159], v[160:161], off
	s_and_b64 vcc, exec, s[2:3]
	s_waitcnt vmcnt(11)
	v_pk_add_f32 v[74:75], v[68:69], 1.0 op_sel_hi:[1,0]
	v_pk_add_f32 v[76:77], v[66:67], 1.0 op_sel_hi:[1,0]
	s_waitcnt vmcnt(9)
	v_pk_mul_f32 v[92:93], v[110:111], s[28:29] op_sel_hi:[1,0]
	v_pk_mul_f32 v[94:95], v[108:109], s[28:29] op_sel_hi:[1,0]
	s_waitcnt vmcnt(8)
	v_pk_add_f32 v[68:69], v[114:115], 1.0 op_sel_hi:[1,0]
	global_load_dwordx4 v[108:111], v[156:157], off offset:256
	global_load_dwordx2 v[114:115], v[154:155], off
	v_pk_mul_f32 v[90:91], v[82:83], s[28:29] op_sel_hi:[1,0]
	v_pk_add_f32 v[66:67], v[116:117], 1.0 op_sel_hi:[1,0]
	s_waitcnt vmcnt(8)
	v_pk_mul_f32 v[82:83], v[144:145], s[28:29] op_sel_hi:[1,0]
	s_waitcnt vmcnt(7)
	v_lshlrev_b32_e32 v116, 16, v146
	v_and_b32_e32 v117, 0xffff0000, v146
	s_waitcnt vmcnt(6)
	v_pk_mul_f32 v[144:145], v[118:119], v[118:119] op_sel:[0,1] op_sel_hi:[1,0]
	v_pk_mul_f32 v[86:87], v[84:85], s[28:29] op_sel_hi:[1,0]
	v_pk_fma_f32 v[116:117], v[118:119], v[116:117], v[144:145] op_sel:[1,0,0] op_sel_hi:[1,1,0] neg_lo:[0,0,1] neg_hi:[0,0,1]
	v_pk_mul_f32 v[70:71], v[124:125], s[28:29] op_sel_hi:[1,0]
	v_pk_mul_f32 v[78:79], v[122:123], s[28:29] op_sel_hi:[1,0]
	v_pk_mul_f32 v[84:85], v[142:143], s[28:29] op_sel_hi:[1,0]
	v_lshlrev_b32_e32 v122, 16, v147
	v_and_b32_e32 v123, 0xffff0000, v147
	v_lshlrev_b32_e32 v124, 16, v148
	v_and_b32_e32 v125, 0xffff0000, v148
	v_lshlrev_b32_e32 v142, 16, v149
	v_and_b32_e32 v143, 0xffff0000, v149
	v_pk_fma_f32 v[116:117], v[90:91], v[116:117], v[94:95]
	v_pk_fma_f32 v[122:123], v[118:119], v[122:123], v[144:145] op_sel:[1,0,0] op_sel_hi:[1,1,0] neg_lo:[0,0,1] neg_hi:[0,0,1]
	v_pk_fma_f32 v[60:61], v[60:61], v[76:77], v[116:117]
	v_pk_fma_f32 v[116:117], v[118:119], v[124:125], v[144:145] op_sel:[1,0,0] op_sel_hi:[1,1,0] neg_lo:[0,0,1] neg_hi:[0,0,1]
	v_pk_fma_f32 v[118:119], v[118:119], v[142:143], v[144:145] op_sel:[1,0,0] op_sel_hi:[1,1,0] neg_lo:[0,0,1] neg_hi:[0,0,1]
	v_pk_fma_f32 v[122:123], v[86:87], v[122:123], v[92:93]
	v_pk_fma_f32 v[118:119], v[70:71], v[118:119], v[82:83]
	v_pk_fma_f32 v[116:117], v[78:79], v[116:117], v[84:85]
	v_pk_fma_f32 v[62:63], v[62:63], v[74:75], v[122:123]
	v_pk_fma_f32 v[118:119], v[58:59], v[66:67], v[118:119]
	v_pk_fma_f32 v[58:59], v[56:57], v[68:69], v[116:117]
	v_cvt_pk_bf16_f32 v56, v60, v61
	v_cvt_pk_bf16_f32 v57, v62, v63
	v_cvt_pk_bf16_f32 v58, v58, v59
	v_cvt_pk_bf16_f32 v59, v118, v119
	global_store_dwordx4 v[120:121], v[56:59], off offset:256
	s_waitcnt vmcnt(5)
; __device__ __forceinline__ u32x4 pack8f(f32x4 lo, f32x4 hi) { u32x4 w; w.x = cvtpk(lo[0], lo[1]); w.y = cvtpk(lo[2], lo[3]); w.z = cvtpk(hi[0], hi[1]); w.w = cvtpk(hi[2], hi[3]); return w; }
;     __device__ __forceinline__ void operator()(const Acc& acc, const Unit& u, int wr, int wc, int fr, int fq) const {
;     ...
;             for (int hf = 0; hf < 2; ++hf) {
;                 u32x4 yv[4]; f32x2 st[4];
; #pragma unroll
;                 for (int m = 0; m < 4; ++m) { const int row = rowb + hf * 128 + m * 16; yv[m] = *(const u32x4*)(y1 + yb + (size_t)(hf * 128 + m * 16) * 256 + bj * 128); st[m] = *(const f32x2*)(stats + (size_t)row * 2); }
; #pragma unroll
;                 for (int m = 0; m < 4; ++m) { const int row = rowb + hf * 128 + m * 16;
;                     f32x4 lo, hi; unpack8(yv[m], lo, hi); const float r = st[m][1], mr = st[m][0] * r;
;                     lo = (lo * r - mr) * G[0] + Bc[0] + gm[0] * acc[hf][bj][m][0]; hi = (hi * r - mr) * G[1] + Bc[1] + gm[1] * acc[hf][bj][m][1];
;                     *(u32x4*)(y2 + yb + (size_t)(hf * 128 + m * 16) * 256 + bj * 128) = pack8f(lo, hi); }
;                 asm volatile("" ::: "memory");
	v_pk_mul_f32 v[116:117], v[126:127], v[126:127] op_sel:[0,1] op_sel_hi:[1,0]
	v_lshlrev_b32_e32 v60, 16, v164
	v_lshlrev_b32_e32 v56, 16, v162
	v_and_b32_e32 v57, 0xffff0000, v162
	v_lshlrev_b32_e32 v58, 16, v163
	v_and_b32_e32 v59, 0xffff0000, v163
	v_pk_fma_f32 v[58:59], v[126:127], v[58:59], v[116:117] op_sel:[1,0,0] op_sel_hi:[1,1,0] neg_lo:[0,0,1] neg_hi:[0,0,1]
	v_pk_fma_f32 v[56:57], v[126:127], v[56:57], v[116:117] op_sel:[1,0,0] op_sel_hi:[1,1,0] neg_lo:[0,0,1] neg_hi:[0,0,1]
	v_and_b32_e32 v61, 0xffff0000, v164
	v_lshlrev_b32_e32 v62, 16, v165
	v_and_b32_e32 v63, 0xffff0000, v165
	v_pk_fma_f32 v[56:57], v[90:91], v[56:57], v[94:95]
	v_pk_fma_f32 v[58:59], v[86:87], v[58:59], v[92:93]
	v_pk_fma_f32 v[52:53], v[52:53], v[76:77], v[56:57]
	v_pk_fma_f32 v[54:55], v[54:55], v[74:75], v[58:59]
	v_pk_fma_f32 v[56:57], v[126:127], v[62:63], v[116:117] op_sel:[1,0,0] op_sel_hi:[1,1,0] neg_lo:[0,0,1] neg_hi:[0,0,1]
	v_pk_fma_f32 v[58:59], v[126:127], v[60:61], v[116:117] op_sel:[1,0,0] op_sel_hi:[1,1,0] neg_lo:[0,0,1] neg_hi:[0,0,1]
	v_pk_fma_f32 v[56:57], v[70:71], v[56:57], v[82:83]
	v_pk_fma_f32 v[58:59], v[78:79], v[58:59], v[84:85]
	v_pk_fma_f32 v[56:57], v[50:51], v[66:67], v[56:57]
	v_pk_fma_f32 v[50:51], v[48:49], v[68:69], v[58:59]
	v_cvt_pk_bf16_f32 v48, v52, v53
	v_cvt_pk_bf16_f32 v49, v54, v55
	v_cvt_pk_bf16_f32 v50, v50, v51
	v_cvt_pk_bf16_f32 v51, v56, v57
	global_store_dwordx4 v[112:113], v[48:51], off offset:256
	s_waitcnt vmcnt(4)
	v_pk_mul_f32 v[56:57], v[158:159], v[158:159] op_sel:[0,1] op_sel_hi:[1,0]
	v_lshlrev_b32_e32 v52, 16, v152
	v_lshlrev_b32_e32 v48, 16, v150
	v_and_b32_e32 v49, 0xffff0000, v150
	v_lshlrev_b32_e32 v50, 16, v151
	v_and_b32_e32 v51, 0xffff0000, v151
	v_pk_fma_f32 v[50:51], v[158:159], v[50:51], v[56:57] op_sel:[1,0,0] op_sel_hi:[1,1,0] neg_lo:[0,0,1] neg_hi:[0,0,1]
	v_pk_fma_f32 v[48:49], v[158:159], v[48:49], v[56:57] op_sel:[1,0,0] op_sel_hi:[1,1,0] neg_lo:[0,0,1] neg_hi:[0,0,1]
	v_and_b32_e32 v53, 0xffff0000, v152
	v_lshlrev_b32_e32 v54, 16, v153
	v_and_b32_e32 v55, 0xffff0000, v153
	v_pk_fma_f32 v[48:49], v[90:91], v[48:49], v[94:95]
	v_pk_fma_f32 v[50:51], v[86:87], v[50:51], v[92:93]
	v_pk_fma_f32 v[44:45], v[44:45], v[76:77], v[48:49]
	v_pk_fma_f32 v[46:47], v[46:47], v[74:75], v[50:51]
	v_pk_fma_f32 v[48:49], v[158:159], v[54:55], v[56:57] op_sel:[1,0,0] op_sel_hi:[1,1,0] neg_lo:[0,0,1] neg_hi:[0,0,1]
	v_pk_fma_f32 v[50:51], v[158:159], v[52:53], v[56:57] op_sel:[1,0,0] op_sel_hi:[1,1,0] neg_lo:[0,0,1] neg_hi:[0,0,1]
	v_pk_fma_f32 v[48:49], v[70:71], v[48:49], v[82:83]
	v_pk_fma_f32 v[50:51], v[78:79], v[50:51], v[84:85]
	v_pk_fma_f32 v[48:49], v[42:43], v[66:67], v[48:49]
	v_pk_fma_f32 v[42:43], v[40:41], v[68:69], v[50:51]
	v_cvt_pk_bf16_f32 v40, v44, v45
	v_cvt_pk_bf16_f32 v41, v46, v47
	v_cvt_pk_bf16_f32 v42, v42, v43
	v_cvt_pk_bf16_f32 v43, v48, v49
	global_store_dwordx4 v[104:105], v[40:43], off offset:256
	s_waitcnt vmcnt(3)
	v_pk_mul_f32 v[48:49], v[114:115], v[114:115] op_sel:[0,1] op_sel_hi:[1,0]
	v_lshlrev_b32_e32 v44, 16, v110
	v_lshlrev_b32_e32 v40, 16, v108
	v_and_b32_e32 v41, 0xffff0000, v108
	v_lshlrev_b32_e32 v42, 16, v109
	v_and_b32_e32 v43, 0xffff0000, v109
	v_pk_fma_f32 v[42:43], v[114:115], v[42:43], v[48:49] op_sel:[1,0,0] op_sel_hi:[1,1,0] neg_lo:[0,0,1] neg_hi:[0,0,1]
	v_pk_fma_f32 v[40:41], v[114:115], v[40:41], v[48:49] op_sel:[1,0,0] op_sel_hi:[1,1,0] neg_lo:[0,0,1] neg_hi:[0,0,1]
	v_and_b32_e32 v45, 0xffff0000, v110
	v_lshlrev_b32_e32 v46, 16, v111
	v_and_b32_e32 v47, 0xffff0000, v111
	v_pk_fma_f32 v[40:41], v[90:91], v[40:41], v[94:95]
	v_pk_fma_f32 v[42:43], v[86:87], v[42:43], v[92:93]
	v_pk_fma_f32 v[36:37], v[36:37], v[76:77], v[40:41]
	v_pk_fma_f32 v[38:39], v[38:39], v[74:75], v[42:43]
	v_pk_fma_f32 v[40:41], v[114:115], v[46:47], v[48:49] op_sel:[1,0,0] op_sel_hi:[1,1,0] neg_lo:[0,0,1] neg_hi:[0,0,1]
	v_pk_fma_f32 v[42:43], v[114:115], v[44:45], v[48:49] op_sel:[1,0,0] op_sel_hi:[1,1,0] neg_lo:[0,0,1] neg_hi:[0,0,1]
	v_pk_fma_f32 v[40:41], v[70:71], v[40:41], v[82:83]
	v_pk_fma_f32 v[42:43], v[78:79], v[42:43], v[84:85]
	v_pk_fma_f32 v[40:41], v[34:35], v[66:67], v[40:41]
	v_pk_fma_f32 v[34:35], v[32:33], v[68:69], v[42:43]
	v_cvt_pk_bf16_f32 v32, v36, v37
	v_cvt_pk_bf16_f32 v33, v38, v39
	v_cvt_pk_bf16_f32 v34, v34, v35
	v_cvt_pk_bf16_f32 v35, v40, v41
	global_store_dwordx4 v[96:97], v[32:35], off offset:256
	global_load_dwordx4 v[32:35], v[98:99], off offset:256
	global_load_dwordx2 v[48:49], v[140:141], off offset:1024
	global_load_dwordx4 v[36:39], v[100:101], off offset:256
	global_load_dwordx2 v[50:51], v[140:141], off offset:1152
	global_load_dwordx4 v[40:43], v[102:103], off offset:256
	global_load_dwordx2 v[52:53], v[140:141], off offset:1280
	global_load_dwordx4 v[44:47], v[106:107], off offset:256
	global_load_dwordx2 v[54:55], v[140:141], off offset:1408
	s_waitcnt vmcnt(7)
	v_lshlrev_b32_e32 v56, 16, v32
	v_and_b32_e32 v57, 0xffff0000, v32
	v_lshlrev_b32_e32 v32, 16, v33
	v_and_b32_e32 v33, 0xffff0000, v33
	s_waitcnt vmcnt(6)
; __device__ __forceinline__ u32x4 pack8f(f32x4 lo, f32x4 hi) { u32x4 w; w.x = cvtpk(lo[0], lo[1]); w.y = cvtpk(lo[2], lo[3]); w.z = cvtpk(hi[0], hi[1]); w.w = cvtpk(hi[2], hi[3]); return w; }
;     __device__ __forceinline__ void operator()(const Acc& acc, const Unit& u, int wr, int wc, int fr, int fq) const {
;     ...
;             for (int hf = 0; hf < 2; ++hf) {
;                 u32x4 yv[4]; f32x2 st[4];
; #pragma unroll
;                 for (int m = 0; m < 4; ++m) { const int row = rowb + hf * 128 + m * 16; yv[m] = *(const u32x4*)(y1 + yb + (size_t)(hf * 128 + m * 16) * 256 + bj * 128); st[m] = *(const f32x2*)(stats + (size_t)row * 2); }
; #pragma unroll
;                 for (int m = 0; m < 4; ++m) { const int row = rowb + hf * 128 + m * 16;
;                     f32x4 lo, hi; unpack8(yv[m], lo, hi); const float r = st[m][1], mr = st[m][0] * r;
;                     lo = (lo * r - mr) * G[0] + Bc[0] + gm[0] * acc[hf][bj][m][0]; hi = (hi * r - mr) * G[1] + Bc[1] + gm[1] * acc[hf][bj][m][1];
;                     *(u32x4*)(y2 + yb + (size_t)(hf * 128 + m * 16) * 256 + bj * 128) = pack8f(lo, hi); }
;                 asm volatile("" ::: "memory");
;             }
;             asm volatile("" ::: "memory");
;         }
;     }
	v_pk_mul_f32 v[60:61], v[48:49], v[48:49] op_sel:[0,1] op_sel_hi:[1,0]
	v_lshlrev_b32_e32 v58, 16, v34
	v_pk_fma_f32 v[32:33], v[48:49], v[32:33], v[60:61] op_sel:[1,0,0] op_sel_hi:[1,1,0] neg_lo:[0,0,1] neg_hi:[0,0,1]
	v_and_b32_e32 v59, 0xffff0000, v34
	v_lshlrev_b32_e32 v34, 16, v35
	v_and_b32_e32 v35, 0xffff0000, v35
	v_pk_fma_f32 v[32:33], v[86:87], v[32:33], v[92:93]
	v_pk_fma_f32 v[56:57], v[48:49], v[56:57], v[60:61] op_sel:[1,0,0] op_sel_hi:[1,1,0] neg_lo:[0,0,1] neg_hi:[0,0,1]
	v_pk_fma_f32 v[30:31], v[30:31], v[74:75], v[32:33]
	v_pk_fma_f32 v[32:33], v[48:49], v[34:35], v[60:61] op_sel:[1,0,0] op_sel_hi:[1,1,0] neg_lo:[0,0,1] neg_hi:[0,0,1]
	v_pk_fma_f32 v[34:35], v[48:49], v[58:59], v[60:61] op_sel:[1,0,0] op_sel_hi:[1,1,0] neg_lo:[0,0,1] neg_hi:[0,0,1]
	v_pk_fma_f32 v[56:57], v[90:91], v[56:57], v[94:95]
	v_pk_fma_f32 v[34:35], v[78:79], v[34:35], v[84:85]
	v_pk_fma_f32 v[32:33], v[70:71], v[32:33], v[82:83]
	v_pk_fma_f32 v[28:29], v[28:29], v[76:77], v[56:57]
	v_pk_fma_f32 v[32:33], v[26:27], v[66:67], v[32:33]
	v_pk_fma_f32 v[26:27], v[24:25], v[68:69], v[34:35]
	v_cvt_pk_bf16_f32 v24, v28, v29
	v_cvt_pk_bf16_f32 v25, v30, v31
	v_cvt_pk_bf16_f32 v26, v26, v27
	v_cvt_pk_bf16_f32 v27, v32, v33
	global_store_dwordx4 v[88:89], v[24:27], off offset:256
	s_waitcnt vmcnt(5)
	v_pk_mul_f32 v[32:33], v[50:51], v[50:51] op_sel:[0,1] op_sel_hi:[1,0]
	v_lshlrev_b32_e32 v28, 16, v38
	v_lshlrev_b32_e32 v24, 16, v36
	v_and_b32_e32 v25, 0xffff0000, v36
	v_lshlrev_b32_e32 v26, 16, v37
	v_and_b32_e32 v27, 0xffff0000, v37
	v_pk_fma_f32 v[26:27], v[50:51], v[26:27], v[32:33] op_sel:[1,0,0] op_sel_hi:[1,1,0] neg_lo:[0,0,1] neg_hi:[0,0,1]
	v_pk_fma_f32 v[24:25], v[50:51], v[24:25], v[32:33] op_sel:[1,0,0] op_sel_hi:[1,1,0] neg_lo:[0,0,1] neg_hi:[0,0,1]
	v_and_b32_e32 v29, 0xffff0000, v38
	v_lshlrev_b32_e32 v30, 16, v39
	v_and_b32_e32 v31, 0xffff0000, v39
	v_pk_fma_f32 v[24:25], v[90:91], v[24:25], v[94:95]
	v_pk_fma_f32 v[26:27], v[86:87], v[26:27], v[92:93]
	v_pk_fma_f32 v[20:21], v[20:21], v[76:77], v[24:25]
	v_pk_fma_f32 v[22:23], v[22:23], v[74:75], v[26:27]
	v_pk_fma_f32 v[24:25], v[50:51], v[30:31], v[32:33] op_sel:[1,0,0] op_sel_hi:[1,1,0] neg_lo:[0,0,1] neg_hi:[0,0,1]
	v_pk_fma_f32 v[26:27], v[50:51], v[28:29], v[32:33] op_sel:[1,0,0] op_sel_hi:[1,1,0] neg_lo:[0,0,1] neg_hi:[0,0,1]
	v_pk_fma_f32 v[24:25], v[70:71], v[24:25], v[82:83]
	v_pk_fma_f32 v[26:27], v[78:79], v[26:27], v[84:85]
	v_pk_fma_f32 v[24:25], v[18:19], v[66:67], v[24:25]
	v_pk_fma_f32 v[18:19], v[16:17], v[68:69], v[26:27]
	v_cvt_pk_bf16_f32 v16, v20, v21
	v_cvt_pk_bf16_f32 v17, v22, v23
	v_cvt_pk_bf16_f32 v18, v18, v19
	v_cvt_pk_bf16_f32 v19, v24, v25
	global_store_dwordx4 v[80:81], v[16:19], off offset:256
	s_waitcnt vmcnt(4)
	v_pk_mul_f32 v[24:25], v[52:53], v[52:53] op_sel:[0,1] op_sel_hi:[1,0]
	v_lshlrev_b32_e32 v20, 16, v42
	v_lshlrev_b32_e32 v16, 16, v40
	v_and_b32_e32 v17, 0xffff0000, v40
	v_lshlrev_b32_e32 v18, 16, v41
	v_and_b32_e32 v19, 0xffff0000, v41
	v_pk_fma_f32 v[18:19], v[52:53], v[18:19], v[24:25] op_sel:[1,0,0] op_sel_hi:[1,1,0] neg_lo:[0,0,1] neg_hi:[0,0,1]
	v_pk_fma_f32 v[16:17], v[52:53], v[16:17], v[24:25] op_sel:[1,0,0] op_sel_hi:[1,1,0] neg_lo:[0,0,1] neg_hi:[0,0,1]
	v_and_b32_e32 v21, 0xffff0000, v42
	v_lshlrev_b32_e32 v22, 16, v43
	v_and_b32_e32 v23, 0xffff0000, v43
	v_pk_fma_f32 v[16:17], v[90:91], v[16:17], v[94:95]
	v_pk_fma_f32 v[18:19], v[86:87], v[18:19], v[92:93]
	v_pk_fma_f32 v[12:13], v[12:13], v[76:77], v[16:17]
	v_pk_fma_f32 v[14:15], v[14:15], v[74:75], v[18:19]
	v_pk_fma_f32 v[16:17], v[52:53], v[22:23], v[24:25] op_sel:[1,0,0] op_sel_hi:[1,1,0] neg_lo:[0,0,1] neg_hi:[0,0,1]
	v_pk_fma_f32 v[18:19], v[52:53], v[20:21], v[24:25] op_sel:[1,0,0] op_sel_hi:[1,1,0] neg_lo:[0,0,1] neg_hi:[0,0,1]
	v_pk_fma_f32 v[16:17], v[70:71], v[16:17], v[82:83]
	v_pk_fma_f32 v[18:19], v[78:79], v[18:19], v[84:85]
	v_pk_fma_f32 v[16:17], v[10:11], v[66:67], v[16:17]
	v_pk_fma_f32 v[10:11], v[8:9], v[68:69], v[18:19]
	v_cvt_pk_bf16_f32 v8, v12, v13
	v_cvt_pk_bf16_f32 v9, v14, v15
	v_cvt_pk_bf16_f32 v10, v10, v11
	v_cvt_pk_bf16_f32 v11, v16, v17
	global_store_dwordx4 v[72:73], v[8:11], off offset:256
	s_waitcnt vmcnt(3)
	v_pk_mul_f32 v[16:17], v[54:55], v[54:55] op_sel:[0,1] op_sel_hi:[1,0]
	v_lshlrev_b32_e32 v12, 16, v46
	v_lshlrev_b32_e32 v8, 16, v44
	v_and_b32_e32 v9, 0xffff0000, v44
	v_lshlrev_b32_e32 v10, 16, v45
	v_and_b32_e32 v11, 0xffff0000, v45
	v_pk_fma_f32 v[10:11], v[54:55], v[10:11], v[16:17] op_sel:[1,0,0] op_sel_hi:[1,1,0] neg_lo:[0,0,1] neg_hi:[0,0,1]
	v_pk_fma_f32 v[8:9], v[54:55], v[8:9], v[16:17] op_sel:[1,0,0] op_sel_hi:[1,1,0] neg_lo:[0,0,1] neg_hi:[0,0,1]
	v_and_b32_e32 v13, 0xffff0000, v46
	v_lshlrev_b32_e32 v14, 16, v47
	v_and_b32_e32 v15, 0xffff0000, v47
	v_pk_fma_f32 v[8:9], v[90:91], v[8:9], v[94:95]
	v_pk_fma_f32 v[10:11], v[86:87], v[10:11], v[92:93]
	v_pk_fma_f32 v[4:5], v[4:5], v[76:77], v[8:9]
	v_pk_fma_f32 v[6:7], v[6:7], v[74:75], v[10:11]
	v_pk_fma_f32 v[8:9], v[54:55], v[14:15], v[16:17] op_sel:[1,0,0] op_sel_hi:[1,1,0] neg_lo:[0,0,1] neg_hi:[0,0,1]
	v_pk_fma_f32 v[10:11], v[54:55], v[12:13], v[16:17] op_sel:[1,0,0] op_sel_hi:[1,1,0] neg_lo:[0,0,1] neg_hi:[0,0,1]
	v_pk_fma_f32 v[8:9], v[70:71], v[8:9], v[82:83]
	v_pk_fma_f32 v[10:11], v[78:79], v[10:11], v[84:85]
	v_pk_fma_f32 v[8:9], v[2:3], v[66:67], v[8:9]
	v_pk_fma_f32 v[2:3], v[0:1], v[68:69], v[10:11]
	v_cvt_pk_bf16_f32 v0, v4, v5
	v_cvt_pk_bf16_f32 v1, v6, v7
	v_cvt_pk_bf16_f32 v2, v2, v3
	v_cvt_pk_bf16_f32 v3, v8, v9
	global_store_dwordx4 v[64:65], v[0:3], off offset:256
	s_cbranch_vccz .LBB0_1274
	s_waitcnt vmcnt(0)
	s_cmpk_gt_u32 s29, 0xff
	s_cbranch_scc1 .LBB0_1285
	s_barrier
